# norm_finish modulation loads hoisted (12 in flight per row), phase-0 GEMV with 64 row loads in flight, Ukv tile order rotated; on top of last-layer ctx skips, MLA pipeline, batched scan, v_rcp
# baseline (speedup 1.0000x reference)
; __device__ __forceinline__ unsigned pk2(float lo, float hi) { f32x2_t v = {lo, hi}; bf16x2_t b = __builtin_convertvector(v, bf16x2_t); return __builtin_bit_cast(unsigned, b); }
; __device__ __forceinline__ void norm_finish(const NormRow& R, const NormPar& P, const float* nw, int lane) {
;     if (P.cp) {
; #pragma unroll
;         for (int j = 0; j < 4; ++j) ((f32x4*)P.cp)[64 * j + lane] = R.v[j];
;     }
;     const float rstd = rsqrtf(wave_sum(R.s) * (1.f / 1024.f) + EPS);
; #pragma unroll
;     for (int j = 0; j < 4; ++j) {
;         const int idx = 64 * j + lane;
;     ...
;         const float y0 = R.v[j][0] * rstd * w[0] * (1.f + a[0]) + bsh[0], y1 = R.v[j][1] * rstd * w[1] * (1.f + a[1]) + bsh[1];
;         const float y2 = R.v[j][2] * rstd * w[2] * (1.f + a[2]) + bsh[2], y3 = R.v[j][3] * rstd * w[3] * (1.f + a[3]) + bsh[3];
;         u32x2 o; o.x = pk2(y0, y1); o.y = pk2(y2, y3);
;         ((u32x2*)P.orow)[idx] = o;
;     }
.LBB0_131:
	s_lshl_b64 s[24:25], s[34:35], 10
	v_mul_f32_e32 v16, v9, v9
	v_mul_f32_e32 v17, v11, v11
	v_fmac_f32_e32 v16, v8, v8
	v_fmac_f32_e32 v17, v10, v10
	s_and_b64 s[0:1], s[28:29], exec
	v_add_f32_e32 v16, v16, v17
	v_mul_f32_e32 v17, v1, v1
	v_mul_f32_e32 v18, v3, v3
	s_cselect_b32 s18, 0x1800, 0
	s_and_b64 s[0:1], s[30:31], exec
	v_fmac_f32_e32 v17, v0, v0
	v_fmac_f32_e32 v18, v2, v2
	s_cselect_b32 s0, s18, 0x3000
	v_add_f32_e32 v17, v17, v18
	s_lshl_b32 s0, s0, 2
	v_readlane_b32 s18, v254, 31
	v_add_f32_e32 v16, v16, v17
	v_mul_f32_e32 v17, v5, v5
	v_mul_f32_e32 v18, v7, v7
	v_readlane_b32 s19, v254, 32
	s_add_u32 s18, s18, s0
	v_fmac_f32_e32 v17, v4, v4
	v_fmac_f32_e32 v18, v6, v6
	s_addc_u32 s19, s19, 0
	v_add_f32_e32 v17, v17, v18
	s_add_u32 s0, s18, 0x4000
	v_add_f32_e32 v16, v16, v17
	v_mul_f32_e32 v17, v13, v13
	v_mul_f32_e32 v18, v15, v15
	s_addc_u32 s1, s19, 0
	v_fmac_f32_e32 v17, v12, v12
	v_fmac_f32_e32 v18, v14, v14
	s_add_u32 s18, s18, 0x3000
	v_add_f32_e32 v17, v17, v18
	s_addc_u32 s19, s19, 0
	global_load_dwordx4 v[18:21], v[48:49], off
	global_load_dwordx4 v[22:25], v58, s[0:1]
	global_load_dwordx4 v[26:29], v58, s[18:19]
	global_load_dwordx4 v[104:107], v[48:49], off offset:1024
	global_load_dwordx4 v[108:111], v68, s[0:1]
	global_load_dwordx4 v[112:115], v68, s[18:19]
	global_load_dwordx4 v[116:119], v[48:49], off offset:2048
	global_load_dwordx4 v[120:123], v69, s[0:1]
	global_load_dwordx4 v[124:127], v69, s[18:19]
	global_load_dwordx4 v[128:131], v[48:49], off offset:3072
	global_load_dwordx4 v[132:135], v70, s[0:1]
	global_load_dwordx4 v[136:139], v70, s[18:19]
	v_add_f32_e32 v16, v16, v17
	ds_bpermute_b32 v17, v37, v16
	s_waitcnt lgkmcnt(0)
	v_add_f32_e32 v16, v16, v17
	ds_bpermute_b32 v17, v41, v16
	s_waitcnt lgkmcnt(0)
	v_add_f32_e32 v16, v16, v17
	ds_bpermute_b32 v17, v64, v16
	s_waitcnt lgkmcnt(0)
	v_add_f32_e32 v16, v16, v17
	ds_bpermute_b32 v17, v65, v16
	s_waitcnt lgkmcnt(0)
	v_add_f32_e32 v16, v16, v17
	ds_bpermute_b32 v17, v66, v16
	s_waitcnt lgkmcnt(0)
	v_add_f32_e32 v16, v16, v17
	ds_bpermute_b32 v17, v67, v16
	s_waitcnt lgkmcnt(0)
	v_add_f32_e32 v16, v16, v17
	v_fmamk_f32 v16, v16, 0x3a800000, v216
	v_cmp_gt_f32_e32 vcc, s33, v16
	v_mul_f32_e32 v17, 0x4b800000, v16
	s_nop 0
	v_cndmask_b32_e32 v16, v16, v17, vcc
	v_rsq_f32_e32 v16, v16
	s_nop 0
	v_mul_f32_e32 v17, 0x45800000, v16
	v_cndmask_b32_e32 v16, v16, v17, vcc
	v_pk_mul_f32 v[8:9], v[8:9], v[16:17] op_sel_hi:[1,0]
	v_pk_mul_f32 v[10:11], v[10:11], v[16:17] op_sel_hi:[1,0]
	v_pk_mul_f32 v[0:1], v[0:1], v[16:17] op_sel_hi:[1,0]
	v_pk_mul_f32 v[2:3], v[2:3], v[16:17] op_sel_hi:[1,0]
	v_pk_mul_f32 v[4:5], v[4:5], v[16:17] op_sel_hi:[1,0]
	v_pk_mul_f32 v[12:13], v[12:13], v[16:17] op_sel_hi:[1,0]
	s_waitcnt vmcnt(0)
	v_pk_mul_f32 v[8:9], v[18:19], v[8:9]
	s_waitcnt vmcnt(1)
	v_pk_add_f32 v[18:19], v[22:23], 1.0 op_sel_hi:[1,0]
	v_pk_mul_f32 v[10:11], v[20:21], v[10:11]
	s_waitcnt vmcnt(0)
	v_pk_fma_f32 v[8:9], v[18:19], v[8:9], v[26:27]
	v_pk_add_f32 v[18:19], v[24:25], 1.0 op_sel_hi:[1,0]
	v_cvt_pk_bf16_f32 v8, v8, v9
	v_pk_fma_f32 v[10:11], v[18:19], v[10:11], v[28:29]
	v_lshl_add_u64 v[26:27], s[24:25], 1, v[52:53]
	v_cvt_pk_bf16_f32 v9, v10, v11
	global_store_dwordx2 v[26:27], v[8:9], off
	s_nop 0
	v_pk_mul_f32 v[0:1], v[104:105], v[0:1]
	v_pk_add_f32 v[8:9], v[108:109], 1.0 op_sel_hi:[1, 0]
	v_pk_mul_f32 v[2:3], v[106:107], v[2:3]
	v_pk_fma_f32 v[0:1], v[8:9], v[0:1], v[112:113]
	v_pk_add_f32 v[8:9], v[110:111], 1.0 op_sel_hi:[1, 0]
	v_cvt_pk_bf16_f32 v0, v0, v1
	v_pk_fma_f32 v[2:3], v[8:9], v[2:3], v[114:115]
	s_nop 0
	v_cvt_pk_bf16_f32 v1, v2, v3
	global_store_dwordx2 v[26:27], v[0:1], off offset:512
	s_nop 0
	v_pk_mul_f32 v[0:1], v[116:117], v[4:5]
	v_pk_add_f32 v[4:5], v[120:121], 1.0 op_sel_hi:[1, 0]
	v_pk_fma_f32 v[0:1], v[0:1], v[4:5], v[124:125]
	v_pk_mul_f32 v[4:5], v[6:7], v[16:17] op_sel_hi:[1, 0]
	v_cvt_pk_bf16_f32 v0, v0, v1
	v_pk_mul_f32 v[2:3], v[118:119], v[4:5]
	v_pk_add_f32 v[4:5], v[122:123], 1.0 op_sel_hi:[1, 0]
	s_nop 0
	v_pk_fma_f32 v[2:3], v[2:3], v[4:5], v[126:127]
	s_nop 0
	v_cvt_pk_bf16_f32 v1, v2, v3
	global_store_dwordx2 v[26:27], v[0:1], off offset:1024
	s_nop 0
	v_pk_mul_f32 v[0:1], v[12:13], v[128:129]
	v_pk_add_f32 v[4:5], v[132:133], 1.0 op_sel_hi:[1, 0]
	v_pk_fma_f32 v[0:1], v[0:1], v[4:5], v[136:137]
	v_pk_mul_f32 v[4:5], v[14:15], v[16:17] op_sel_hi:[1, 0]
	v_cvt_pk_bf16_f32 v0, v0, v1
	v_pk_mul_f32 v[2:3], v[4:5], v[130:131]
	v_pk_add_f32 v[4:5], v[134:135], 1.0 op_sel_hi:[1, 0]
	s_nop 0
	v_pk_fma_f32 v[2:3], v[2:3], v[4:5], v[138:139]
	s_nop 0
	v_cvt_pk_bf16_f32 v1, v2, v3
	global_store_dwordx2 v[26:27], v[0:1], off offset:1536

; __device__ __forceinline__ unsigned pk2(float lo, float hi) { f32x2_t v = {lo, hi}; bf16x2_t b = __builtin_convertvector(v, bf16x2_t); return __builtin_bit_cast(unsigned, b); }
; __device__ __forceinline__ void norm_load(NormRow& R, const NormPar& P, int lane) {
;     const f32x4* xr = (const f32x4*)P.src + lane; R.s = 0.f;
; #pragma unroll
;     for (int j = 0; j < 4; ++j) { R.v[j] = xr[64 * j];
;         if (P.part) { f32x4 a = (f32x4){0.f, 0.f, 0.f, 0.f};
;             for (int q = 0; q < P.nsl; ++q) a = a + ((const f32x4*)(P.part + (size_t)q * 512 * 1024))[64 * j + lane];
;             R.v[j] = R.v[j] + ((const f32x4*)P.gv)[64 * j + lane] * a; }
;         R.s += (R.v[j][0] * R.v[j][0] + R.v[j][1] * R.v[j][1]) + (R.v[j][2] * R.v[j][2] + R.v[j][3] * R.v[j][3]); }
; }
; __device__ __forceinline__ void norm_finish(const NormRow& R, const NormPar& P, const float* nw, int lane) {
;     if (P.cp) {
; #pragma unroll
;         for (int j = 0; j < 4; ++j) ((f32x4*)P.cp)[64 * j + lane] = R.v[j];
;     }
;     const float rstd = rsqrtf(wave_sum(R.s) * (1.f / 1024.f) + EPS);
; #pragma unroll
;     for (int j = 0; j < 4; ++j) {
;         const int idx = 64 * j + lane;
;     ...
;         const float y0 = R.v[j][0] * rstd * w[0] * (1.f + a[0]) + bsh[0], y1 = R.v[j][1] * rstd * w[1] * (1.f + a[1]) + bsh[1];
;         const float y2 = R.v[j][2] * rstd * w[2] * (1.f + a[2]) + bsh[2], y3 = R.v[j][3] * rstd * w[3] * (1.f + a[3]) + bsh[3];
;         u32x2 o; o.x = pk2(y0, y1); o.y = pk2(y2, y3);
;         ((u32x2*)P.orow)[idx] = o;
;     }
.LBB0_148:
	s_and_b64 s[0:1], s[36:37], exec
	s_cselect_b32 s18, 0x1800, 0
	s_and_b64 s[0:1], s[44:45], exec
	s_cselect_b32 s0, s18, 0x3000
	s_lshl_b32 s0, s0, 2
	v_readlane_b32 s18, v254, 31
	v_readlane_b32 s19, v254, 32
	s_add_u32 s18, s18, s0
	s_addc_u32 s19, s19, 0
	s_add_u32 s0, s18, 0x4000
	s_addc_u32 s1, s19, 0
	s_add_u32 s18, s18, 0x3000
	s_addc_u32 s19, s19, 0
	global_load_dwordx4 v[72:75], v[48:49], off
	global_load_dwordx4 v[76:79], v58, s[0:1]
	global_load_dwordx4 v[80:83], v58, s[18:19]
	global_load_dwordx4 v[104:107], v[48:49], off offset:1024
	global_load_dwordx4 v[108:111], v68, s[0:1]
	global_load_dwordx4 v[112:115], v68, s[18:19]
	global_load_dwordx4 v[116:119], v[48:49], off offset:2048
	global_load_dwordx4 v[120:123], v69, s[0:1]
	global_load_dwordx4 v[124:127], v69, s[18:19]
	global_load_dwordx4 v[128:131], v[48:49], off offset:3072
	global_load_dwordx4 v[132:135], v70, s[0:1]
	global_load_dwordx4 v[136:139], v70, s[18:19]
	s_waitcnt vmcnt(0)
	v_mul_f32_e32 v59, v25, v25
	v_mul_f32_e32 v62, v27, v27
	v_fmac_f32_e32 v59, v24, v24
	v_fmac_f32_e32 v62, v26, v26
	v_add_f32_e32 v59, v59, v62
	v_mul_f32_e32 v62, v17, v17
	v_mul_f32_e32 v63, v19, v19
	v_fmac_f32_e32 v62, v16, v16
	v_fmac_f32_e32 v63, v18, v18
	v_add_f32_e32 v62, v62, v63
	v_add_f32_e32 v59, v59, v62
	v_mul_f32_e32 v62, v21, v21
	v_mul_f32_e32 v63, v23, v23
	v_fmac_f32_e32 v62, v20, v20
	v_fmac_f32_e32 v63, v22, v22
	v_add_f32_e32 v62, v62, v63
	v_add_f32_e32 v59, v59, v62
	v_mul_f32_e32 v62, v29, v29
	v_mul_f32_e32 v63, v31, v31
	v_fmac_f32_e32 v62, v28, v28
	v_fmac_f32_e32 v63, v30, v30
	v_add_f32_e32 v62, v62, v63
	v_add_f32_e32 v59, v59, v62
	ds_bpermute_b32 v62, v37, v59
	s_mov_b32 s24, 0x68a0000
	s_waitcnt lgkmcnt(0)
	v_add_f32_e32 v59, v59, v62
	ds_bpermute_b32 v62, v41, v59
	s_waitcnt lgkmcnt(0)
	v_add_f32_e32 v59, v59, v62
	ds_bpermute_b32 v62, v64, v59
	s_waitcnt lgkmcnt(0)
	v_add_f32_e32 v59, v59, v62
	ds_bpermute_b32 v62, v65, v59
	s_waitcnt lgkmcnt(0)
	v_add_f32_e32 v59, v59, v62
	ds_bpermute_b32 v62, v66, v59
	s_waitcnt lgkmcnt(0)
	v_add_f32_e32 v59, v59, v62
	ds_bpermute_b32 v62, v67, v59
	s_waitcnt lgkmcnt(0)
	v_add_f32_e32 v59, v59, v62
	v_fmamk_f32 v59, v59, 0x3a800000, v216
	v_cmp_gt_f32_e32 vcc, s33, v59
	v_mul_f32_e32 v62, 0x4b800000, v59
	s_nop 0
	v_cndmask_b32_e32 v59, v59, v62, vcc
	v_rsq_f32_e32 v59, v59
	s_nop 0
	v_mul_f32_e32 v62, 0x45800000, v59
	v_cndmask_b32_e32 v62, v59, v62, vcc
	v_pk_mul_f32 v[24:25], v[24:25], v[62:63] op_sel_hi:[1,0]
	v_pk_mul_f32 v[26:27], v[26:27], v[62:63] op_sel_hi:[1,0]
	v_pk_mul_f32 v[16:17], v[16:17], v[62:63] op_sel_hi:[1,0]
	v_pk_mul_f32 v[18:19], v[18:19], v[62:63] op_sel_hi:[1,0]
	v_pk_mul_f32 v[20:21], v[20:21], v[62:63] op_sel_hi:[1,0]
	v_pk_mul_f32 v[28:29], v[28:29], v[62:63] op_sel_hi:[1,0]
	v_pk_mul_f32 v[24:25], v[72:73], v[24:25]
	v_pk_add_f32 v[72:73], v[76:77], 1.0 op_sel_hi:[1,0]
	v_pk_mul_f32 v[26:27], v[74:75], v[26:27]
	v_pk_fma_f32 v[24:25], v[72:73], v[24:25], v[80:81]
	v_pk_add_f32 v[72:73], v[78:79], 1.0 op_sel_hi:[1,0]
	v_cvt_pk_bf16_f32 v24, v24, v25
	v_pk_fma_f32 v[26:27], v[72:73], v[26:27], v[82:83]
	s_nop 0
	v_cvt_pk_bf16_f32 v25, v26, v27
	v_lshl_add_u64 v[26:27], s[4:5], 0, v[54:55]
	v_add_co_u32_e32 v80, vcc, s24, v26
	s_nop 1
	v_addc_co_u32_e32 v81, vcc, 0, v27, vcc
	global_store_dwordx2 v[80:81], v[24:25], off
	s_nop 0
	s_andn2_b64 vcc, exec, s[42:43]
	v_pk_mul_f32 v[16:17], v[104:105], v[16:17]
	v_pk_add_f32 v[24:25], v[108:109], 1.0 op_sel_hi:[1, 0]
	v_pk_mul_f32 v[18:19], v[106:107], v[18:19]
	v_pk_fma_f32 v[16:17], v[24:25], v[16:17], v[112:113]
	v_pk_add_f32 v[24:25], v[110:111], 1.0 op_sel_hi:[1, 0]
	v_cvt_pk_bf16_f32 v16, v16, v17
	v_pk_fma_f32 v[18:19], v[24:25], v[18:19], v[114:115]
	s_nop 0
	v_cvt_pk_bf16_f32 v17, v18, v19
	global_store_dwordx2 v[80:81], v[16:17], off offset:512
	s_nop 0
	v_pk_mul_f32 v[16:17], v[116:117], v[20:21]
	v_pk_add_f32 v[20:21], v[120:121], 1.0 op_sel_hi:[1, 0]
	v_pk_fma_f32 v[16:17], v[16:17], v[20:21], v[124:125]
	v_pk_mul_f32 v[20:21], v[22:23], v[62:63] op_sel_hi:[1, 0]
	v_cvt_pk_bf16_f32 v16, v16, v17
	v_pk_mul_f32 v[18:19], v[118:119], v[20:21]
	v_pk_add_f32 v[20:21], v[122:123], 1.0 op_sel_hi:[1, 0]
	s_nop 0
	v_pk_fma_f32 v[18:19], v[18:19], v[20:21], v[126:127]
	s_nop 0
	v_cvt_pk_bf16_f32 v17, v18, v19
	global_store_dwordx2 v[80:81], v[16:17], off offset:1024
	s_nop 0
	v_pk_mul_f32 v[16:17], v[28:29], v[128:129]
	v_pk_add_f32 v[20:21], v[132:133], 1.0 op_sel_hi:[1, 0]
	v_pk_fma_f32 v[16:17], v[16:17], v[20:21], v[136:137]
	v_pk_mul_f32 v[20:21], v[30:31], v[62:63] op_sel_hi:[1, 0]
	v_cvt_pk_bf16_f32 v16, v16, v17
	v_pk_mul_f32 v[18:19], v[20:21], v[130:131]
	v_pk_add_f32 v[20:21], v[134:135], 1.0 op_sel_hi:[1, 0]
	s_nop 0
	v_pk_fma_f32 v[18:19], v[18:19], v[20:21], v[138:139]
	s_nop 0
	v_cvt_pk_bf16_f32 v17, v18, v19
	global_store_dwordx2 v[80:81], v[16:17], off offset:1536
	s_cbranch_vccnz .LBB0_132
	s_and_b64 vcc, exec, s[38:39]
	s_cbranch_vccnz .LBB0_131
	global_store_dwordx4 v[60:61], v[8:11], off
	global_store_dwordx4 v[60:61], v[0:3], off offset:1024
	global_store_dwordx4 v[60:61], v[4:7], off offset:2048
	global_store_dwordx4 v[60:61], v[12:15], off offset:3072
	s_branch .LBB0_131

; #define PG8_LAS __attribute__((address_space(3)))
;     __device__ void init(int N, int G_, int c_) { S.init(64 * 256, N, G_, c_); }
;     __device__ bool next(int i, pg8::Unit& u) const { if (!S.next(i, u)) return false; u.pm = (u.pm < 32) ? u.pm + 1 : u.pm + 2; return true; }
;     __host__ __device__ bool next(int i, Unit& u) const {
;         const long L = (long)i * G + c; if (L >= nwg) return false;
;         int wgid = (int)L; { const int q = nwg / NXCD, r = nwg % NXCD, xcd = wgid % NXCD, off = wgid / NXCD; wgid = (xcd < r ? xcd * (q + 1) : r * (q + 1) + (xcd - r) * q) + off; }
;         const int nig = WGM * nN, gid = wgid / nig, fm = gid * WGM, gsz = (nM - fm) < WGM ? (nM - fm) : WGM;
;         u.pm = fm + ((wgid % nig) % gsz); u.pn = (wgid % nig) / gsz; u.kb = 0; return true;
; template <class Epi> __device__ __forceinline__ void run_gemm(unsigned char* lds, const bf16_t* A, const bf16_t* Bt, int M, int N, int K, const Epi& E) {
;     asm volatile("" : "+s"(K), "+s"(M), "+s"(N));
;     int gd_ = (int)gridDim.x, bi_ = (int)blockIdx.x; asm volatile("" : "+s"(gd_), "+s"(bi_));
;     pg8::Gemm g{A, Bt, M, N, K, K}; pg8::StaticOrder S; S.init(M, N, gd_, bi_);
;     pg8::gemm_phase<Epi, pg8::StaticOrder, true, true>((PG8_LAS unsigned char*)lds, g, S, E);
.LBB0_571:
	s_movk_i32 s0, 0x4200
	s_movk_i32 s1, 0x400
	s_movk_i32 s24, 0x100
	v_readlane_b32 s2, v253, 0
	s_mov_b32 s13, s2
	s_ashr_i32 s2, s0, 31
	s_lshr_b32 s2, s2, 24
	s_add_i32 s0, s0, s2
	s_ashr_i32 s27, s0, 8
	s_ashr_i32 s0, s1, 31
	s_lshr_b32 s0, s0, 24
	s_add_i32 s1, s1, s0
	s_ashr_i32 s38, s1, 8
	s_add_i32 s26, s81, 56
	s_sub_i32 s0, s26, s13
	s_cmp_ge_u32 s26, s13
	s_cselect_b32 s26, s0, s26
	s_mul_i32 s2, s38, s27
	v_readlane_b32 s3, v253, 1
	v_mov_b32_e32 v18, v203
	s_cmp_lt_i32 s26, s2
	s_cselect_b64 s[0:1], -1, 0
	s_cmp_ge_i32 s26, s2
	v_readfirstlane_b32 s3, v18
	s_cbranch_scc1 .LBB0_577
	s_ashr_i32 s10, s2, 31
	s_lshr_b32 s10, s10, 29
	s_add_i32 s10, s2, s10
	s_ashr_i32 s18, s10, 3
	s_and_b32 s10, s10, -8
	s_sub_i32 s19, s2, s10
	s_ashr_i32 s10, s26, 31
	s_lshr_b32 s10, s10, 29
	s_add_i32 s14, s26, s10
	s_and_b32 s10, s14, -8
	s_sub_i32 s16, s26, s10
	s_add_i32 s17, s18, 1
	s_cmp_ge_i32 s16, s19
	s_mov_b64 s[10:11], -1
	s_cbranch_scc0 .LBB0_574
	s_sub_i32 s11, s16, s19
	s_mul_i32 s10, s17, s19
	s_mul_i32 s11, s11, s18
	s_add_i32 s15, s11, s10
	s_mov_b64 s[10:11], 0

; __device__ __forceinline__ unsigned pk2(float lo, float hi) { f32x2_t v = {lo, hi}; bf16x2_t b = __builtin_convertvector(v, bf16x2_t); return __builtin_bit_cast(unsigned, b); }
; __device__ __forceinline__ void norm_finish(const NormRow& R, const NormPar& P, const float* nw, int lane) {
;     if (P.cp) {
; #pragma unroll
;         for (int j = 0; j < 4; ++j) ((f32x4*)P.cp)[64 * j + lane] = R.v[j];
;     }
;     const float rstd = rsqrtf(wave_sum(R.s) * (1.f / 1024.f) + EPS);
; #pragma unroll
;     for (int j = 0; j < 4; ++j) {
;         const int idx = 64 * j + lane;
;     ...
;         const float y0 = R.v[j][0] * rstd * w[0] * (1.f + a[0]) + bsh[0], y1 = R.v[j][1] * rstd * w[1] * (1.f + a[1]) + bsh[1];
;         const float y2 = R.v[j][2] * rstd * w[2] * (1.f + a[2]) + bsh[2], y3 = R.v[j][3] * rstd * w[3] * (1.f + a[3]) + bsh[3];
;         u32x2 o; o.x = pk2(y0, y1); o.y = pk2(y2, y3);
;         ((u32x2*)P.orow)[idx] = o;
;     }
.LBB0_2180:
	s_lshl_b64 s[24:25], s[40:41], 10
	s_and_b64 s[0:1], s[30:31], exec
	s_cselect_b32 s17, 0x1800, 0
	s_and_b64 s[0:1], s[34:35], exec
	s_cselect_b32 s0, s17, 0x3000
	s_lshl_b32 s0, s0, 2
	v_readlane_b32 s18, v254, 31
	v_readlane_b32 s19, v254, 32
	s_add_u32 s0, s18, s0
	s_addc_u32 s1, s19, 0
	s_add_u32 s18, s0, 0x1000
	global_load_dwordx4 v[0:3], v[32:33], off
	s_addc_u32 s19, s1, 0
	global_load_dwordx4 v[4:7], v42, s[18:19]
	global_load_dwordx4 v[8:11], v42, s[0:1]
	global_load_dwordx4 v[104:107], v[32:33], off offset:1024
	global_load_dwordx4 v[108:111], v52, s[18:19]
	global_load_dwordx4 v[112:115], v42, s[0:1] offset:1024
	global_load_dwordx4 v[116:119], v[32:33], off offset:2048
	global_load_dwordx4 v[120:123], v53, s[18:19]
	global_load_dwordx4 v[124:127], v42, s[0:1] offset:2048
	global_load_dwordx4 v[128:131], v[32:33], off offset:3072
	global_load_dwordx4 v[132:135], v54, s[18:19]
	global_load_dwordx4 v[136:139], v42, s[0:1] offset:3072
	v_mul_f32_e32 v12, v17, v17
	v_mul_f32_e32 v13, v19, v19
	v_mul_f32_e32 v14, v21, v21
	v_mul_f32_e32 v15, v23, v23
	v_mul_f32_e32 v43, v25, v25
	v_mul_f32_e32 v55, v27, v27
	v_fmac_f32_e32 v12, v16, v16
	v_fmac_f32_e32 v13, v18, v18
	v_fmac_f32_e32 v14, v20, v20
	v_fmac_f32_e32 v15, v22, v22
	v_mul_f32_e32 v56, v29, v29
	v_mul_f32_e32 v57, v31, v31
	v_fmac_f32_e32 v43, v24, v24
	v_fmac_f32_e32 v55, v26, v26
	v_add_f32_e32 v12, v12, v13
	v_add_f32_e32 v13, v14, v15
	v_fmac_f32_e32 v56, v28, v28
	v_fmac_f32_e32 v57, v30, v30
	v_add_f32_e32 v14, v43, v55
	v_add_f32_e32 v12, v12, v13
	v_add_f32_e32 v15, v56, v57
	v_add_f32_e32 v12, v12, v14
	v_add_f32_e32 v12, v12, v15
	ds_bpermute_b32 v13, v37, v12
	s_waitcnt lgkmcnt(0)
	v_add_f32_e32 v12, v12, v13
	ds_bpermute_b32 v13, v41, v12
	s_waitcnt lgkmcnt(0)
	v_add_f32_e32 v12, v12, v13
	ds_bpermute_b32 v13, v48, v12
	s_waitcnt lgkmcnt(0)
	v_add_f32_e32 v12, v12, v13
	ds_bpermute_b32 v13, v49, v12
	s_waitcnt lgkmcnt(0)
	v_add_f32_e32 v12, v12, v13
	ds_bpermute_b32 v13, v50, v12
	s_waitcnt lgkmcnt(0)
	v_add_f32_e32 v12, v12, v13
	ds_bpermute_b32 v13, v51, v12
	s_waitcnt lgkmcnt(0)
	v_add_f32_e32 v12, v12, v13
	v_fmamk_f32 v12, v12, 0x3a800000, v216
	v_mul_f32_e32 v13, 0x4b800000, v12
	v_cmp_gt_f32_e32 vcc, s33, v12
	s_waitcnt vmcnt(0)
	v_pk_add_f32 v[4:5], v[4:5], 1.0 op_sel_hi:[1,0]
	v_cndmask_b32_e32 v12, v12, v13, vcc
	v_rsq_f32_e32 v14, v12
	v_pk_add_f32 v[6:7], v[6:7], 1.0 op_sel_hi:[1,0]
	v_lshl_add_u64 v[12:13], s[24:25], 1, v[34:35]
	v_mul_f32_e32 v15, 0x45800000, v14
	v_cndmask_b32_e32 v14, v14, v15, vcc
	v_pk_mul_f32 v[16:17], v[16:17], v[14:15] op_sel_hi:[1,0]
	v_pk_mul_f32 v[18:19], v[18:19], v[14:15] op_sel_hi:[1,0]
	v_pk_mul_f32 v[0:1], v[0:1], v[16:17]
	v_pk_mul_f32 v[2:3], v[2:3], v[18:19]
	s_waitcnt vmcnt(0)
	v_pk_fma_f32 v[0:1], v[4:5], v[0:1], v[8:9]
	v_pk_fma_f32 v[2:3], v[6:7], v[2:3], v[10:11]
	v_cvt_pk_bf16_f32 v0, v0, v1
	v_cvt_pk_bf16_f32 v1, v2, v3
	global_store_dwordx2 v[12:13], v[0:1], off
	s_nop 0
	v_pk_mul_f32 v[16:17], v[20:21], v[14:15] op_sel_hi:[1, 0]
	v_pk_mul_f32 v[18:19], v[22:23], v[14:15] op_sel_hi:[1, 0]
	v_pk_mul_f32 v[0:1], v[104:105], v[16:17]
	v_pk_add_f32 v[4:5], v[108:109], 1.0 op_sel_hi:[1, 0]
	v_pk_mul_f32 v[2:3], v[106:107], v[18:19]
	v_pk_add_f32 v[6:7], v[110:111], 1.0 op_sel_hi:[1, 0]
	v_pk_fma_f32 v[0:1], v[4:5], v[0:1], v[112:113]
	v_pk_fma_f32 v[2:3], v[6:7], v[2:3], v[114:115]
	v_cvt_pk_bf16_f32 v0, v0, v1
	v_cvt_pk_bf16_f32 v1, v2, v3
	global_store_dwordx2 v[12:13], v[0:1], off offset:512
	s_nop 0
	v_pk_mul_f32 v[16:17], v[24:25], v[14:15] op_sel_hi:[1, 0]
	v_pk_mul_f32 v[18:19], v[26:27], v[14:15] op_sel_hi:[1, 0]
	v_pk_mul_f32 v[0:1], v[116:117], v[16:17]
	v_pk_add_f32 v[4:5], v[120:121], 1.0 op_sel_hi:[1, 0]
	v_pk_mul_f32 v[2:3], v[118:119], v[18:19]
	v_pk_add_f32 v[6:7], v[122:123], 1.0 op_sel_hi:[1, 0]
	v_pk_fma_f32 v[0:1], v[0:1], v[4:5], v[124:125]
	v_pk_fma_f32 v[2:3], v[2:3], v[6:7], v[126:127]
	v_cvt_pk_bf16_f32 v0, v0, v1
	v_cvt_pk_bf16_f32 v1, v2, v3
	global_store_dwordx2 v[12:13], v[0:1], off offset:1024
	s_nop 0
	v_pk_mul_f32 v[16:17], v[28:29], v[14:15] op_sel_hi:[1, 0]
	v_pk_mul_f32 v[14:15], v[30:31], v[14:15] op_sel_hi:[1, 0]
	v_pk_mul_f32 v[0:1], v[16:17], v[128:129]
	v_pk_add_f32 v[4:5], v[132:133], 1.0 op_sel_hi:[1, 0]
	v_pk_mul_f32 v[2:3], v[14:15], v[130:131]
	v_pk_add_f32 v[6:7], v[134:135], 1.0 op_sel_hi:[1, 0]
	v_pk_fma_f32 v[0:1], v[0:1], v[4:5], v[136:137]
	v_pk_fma_f32 v[2:3], v[2:3], v[6:7], v[138:139]
	v_cvt_pk_bf16_f32 v0, v0, v1
	v_cvt_pk_bf16_f32 v1, v2, v3
	global_store_dwordx2 v[12:13], v[0:1], off offset:1536

; __device__ __forceinline__ unsigned pk2(float lo, float hi) { f32x2_t v = {lo, hi}; bf16x2_t b = __builtin_convertvector(v, bf16x2_t); return __builtin_bit_cast(unsigned, b); }
; __device__ __forceinline__ void norm_load(NormRow& R, const NormPar& P, int lane) {
;     const f32x4* xr = (const f32x4*)P.src + lane; R.s = 0.f;
; #pragma unroll
;     for (int j = 0; j < 4; ++j) { R.v[j] = xr[64 * j];
;         if (P.part) { f32x4 a = (f32x4){0.f, 0.f, 0.f, 0.f};
;             for (int q = 0; q < P.nsl; ++q) a = a + ((const f32x4*)(P.part + (size_t)q * 512 * 1024))[64 * j + lane];
;             R.v[j] = R.v[j] + ((const f32x4*)P.gv)[64 * j + lane] * a; }
;         R.s += (R.v[j][0] * R.v[j][0] + R.v[j][1] * R.v[j][1]) + (R.v[j][2] * R.v[j][2] + R.v[j][3] * R.v[j][3]); }
; }
; __device__ __forceinline__ void norm_finish(const NormRow& R, const NormPar& P, const float* nw, int lane) {
;     if (P.cp) {
; #pragma unroll
;         for (int j = 0; j < 4; ++j) ((f32x4*)P.cp)[64 * j + lane] = R.v[j];
;     }
;     const float rstd = rsqrtf(wave_sum(R.s) * (1.f / 1024.f) + EPS);
; #pragma unroll
;     for (int j = 0; j < 4; ++j) {
;         const int idx = 64 * j + lane;
;     ...
;         const float y0 = R.v[j][0] * rstd * w[0] * (1.f + a[0]) + bsh[0], y1 = R.v[j][1] * rstd * w[1] * (1.f + a[1]) + bsh[1];
;         const float y2 = R.v[j][2] * rstd * w[2] * (1.f + a[2]) + bsh[2], y3 = R.v[j][3] * rstd * w[3] * (1.f + a[3]) + bsh[3];
;         u32x2 o; o.x = pk2(y0, y1); o.y = pk2(y2, y3);
;         ((u32x2*)P.orow)[idx] = o;
;     }
.LBB0_2215:
	s_and_b64 s[0:1], s[46:47], exec
	s_cselect_b32 s17, 0x1800, 0
	s_and_b64 s[0:1], s[48:49], exec
	s_cselect_b32 s0, s17, 0x3000
	s_lshl_b32 s0, s0, 2
	v_readlane_b32 s18, v254, 31
	v_readlane_b32 s19, v254, 32
	s_add_u32 s0, s18, s0
	s_addc_u32 s1, s19, 0
	s_add_u32 s18, s0, 0x1000
	global_load_dwordx4 v[56:59], v[32:33], off
	s_addc_u32 s19, s1, 0
	global_load_dwordx4 v[60:63], v42, s[18:19]
	global_load_dwordx4 v[64:67], v42, s[0:1]
	global_load_dwordx4 v[104:107], v[32:33], off offset:1024
	global_load_dwordx4 v[108:111], v52, s[18:19]
	global_load_dwordx4 v[112:115], v42, s[0:1] offset:1024
	global_load_dwordx4 v[116:119], v[32:33], off offset:2048
	global_load_dwordx4 v[120:123], v53, s[18:19]
	global_load_dwordx4 v[124:127], v42, s[0:1] offset:2048
	global_load_dwordx4 v[128:131], v[32:33], off offset:3072
	global_load_dwordx4 v[132:135], v54, s[18:19]
	global_load_dwordx4 v[136:139], v42, s[0:1] offset:3072
	s_waitcnt vmcnt(0)
	v_mul_f32_e32 v43, v1, v1
	v_mul_f32_e32 v55, v3, v3
	v_mul_f32_e32 v68, v5, v5
	v_mul_f32_e32 v69, v7, v7
	v_mul_f32_e32 v70, v9, v9
	v_mul_f32_e32 v71, v11, v11
	v_fmac_f32_e32 v43, v0, v0
	v_fmac_f32_e32 v55, v2, v2
	v_fmac_f32_e32 v68, v4, v4
	v_fmac_f32_e32 v69, v6, v6
	v_mul_f32_e32 v72, v13, v13
	v_mul_f32_e32 v73, v15, v15
	v_fmac_f32_e32 v70, v8, v8
	v_fmac_f32_e32 v71, v10, v10
	v_add_f32_e32 v43, v43, v55
	v_add_f32_e32 v55, v68, v69
	v_fmac_f32_e32 v72, v12, v12
	v_fmac_f32_e32 v73, v14, v14
	v_add_f32_e32 v68, v70, v71
	v_add_f32_e32 v43, v43, v55
	v_add_f32_e32 v69, v72, v73
	v_add_f32_e32 v43, v43, v68
	v_add_f32_e32 v43, v43, v69
	ds_bpermute_b32 v55, v37, v43
	v_lshl_add_u64 v[68:69], s[4:5], 0, v[38:39]
	s_mov_b32 s17, 0x68a0000
	v_add_co_u32_e64 v68, s[38:39], s17, v68
	s_waitcnt lgkmcnt(0)
	v_add_f32_e32 v43, v43, v55
	ds_bpermute_b32 v55, v41, v43
	v_addc_co_u32_e64 v69, s[38:39], 0, v69, s[38:39]
	s_waitcnt lgkmcnt(0)
	v_add_f32_e32 v43, v43, v55
	ds_bpermute_b32 v55, v48, v43
	s_waitcnt lgkmcnt(0)
	v_add_f32_e32 v43, v43, v55
	ds_bpermute_b32 v55, v49, v43
	s_waitcnt lgkmcnt(0)
	v_add_f32_e32 v43, v43, v55
	ds_bpermute_b32 v55, v50, v43
	s_waitcnt lgkmcnt(0)
	v_add_f32_e32 v43, v43, v55
	ds_bpermute_b32 v55, v51, v43
	s_waitcnt lgkmcnt(0)
	v_add_f32_e32 v43, v43, v55
	v_fmamk_f32 v43, v43, 0x3a800000, v216
	v_mul_f32_e32 v55, 0x4b800000, v43
	v_cmp_gt_f32_e32 vcc, s33, v43
	s_nop 1
	v_cndmask_b32_e32 v43, v43, v55, vcc
	v_rsq_f32_e32 v43, v43
	s_nop 0
	v_mul_f32_e32 v55, 0x45800000, v43
	v_cndmask_b32_e32 v70, v43, v55, vcc
	v_pk_mul_f32 v[0:1], v[0:1], v[70:71] op_sel_hi:[1,0]
	v_pk_mul_f32 v[2:3], v[2:3], v[70:71] op_sel_hi:[1,0]
	v_pk_mul_f32 v[4:5], v[4:5], v[70:71] op_sel_hi:[1,0]
	v_pk_mul_f32 v[6:7], v[6:7], v[70:71] op_sel_hi:[1,0]
	v_pk_mul_f32 v[8:9], v[8:9], v[70:71] op_sel_hi:[1,0]
	v_pk_mul_f32 v[10:11], v[10:11], v[70:71] op_sel_hi:[1,0]
	v_pk_mul_f32 v[0:1], v[56:57], v[0:1]
	v_pk_mul_f32 v[2:3], v[58:59], v[2:3]
	v_pk_add_f32 v[56:57], v[60:61], 1.0 op_sel_hi:[1,0]
	v_pk_add_f32 v[58:59], v[62:63], 1.0 op_sel_hi:[1,0]
	v_pk_fma_f32 v[0:1], v[56:57], v[0:1], v[64:65]
	v_pk_fma_f32 v[2:3], v[58:59], v[2:3], v[66:67]
	v_cvt_pk_bf16_f32 v0, v0, v1
	v_cvt_pk_bf16_f32 v1, v2, v3
	global_store_dwordx2 v[68:69], v[0:1], off
	s_nop 0
	v_pk_mul_f32 v[12:13], v[12:13], v[70:71] op_sel_hi:[1, 0]
	v_pk_mul_f32 v[14:15], v[14:15], v[70:71] op_sel_hi:[1, 0]
	s_andn2_b64 vcc, exec, s[42:43]
	v_pk_mul_f32 v[0:1], v[104:105], v[4:5]
	v_pk_add_f32 v[4:5], v[108:109], 1.0 op_sel_hi:[1, 0]
	v_pk_mul_f32 v[2:3], v[106:107], v[6:7]
	v_pk_add_f32 v[6:7], v[110:111], 1.0 op_sel_hi:[1, 0]
	v_pk_fma_f32 v[0:1], v[4:5], v[0:1], v[112:113]
	v_pk_fma_f32 v[2:3], v[6:7], v[2:3], v[114:115]
	v_cvt_pk_bf16_f32 v0, v0, v1
	v_cvt_pk_bf16_f32 v1, v2, v3
	global_store_dwordx2 v[68:69], v[0:1], off offset:512
	s_nop 0
	v_pk_mul_f32 v[0:1], v[116:117], v[8:9]
	v_pk_add_f32 v[4:5], v[120:121], 1.0 op_sel_hi:[1, 0]
	v_pk_mul_f32 v[2:3], v[118:119], v[10:11]
	v_pk_add_f32 v[6:7], v[122:123], 1.0 op_sel_hi:[1, 0]
	v_pk_fma_f32 v[0:1], v[0:1], v[4:5], v[124:125]
	v_pk_fma_f32 v[2:3], v[2:3], v[6:7], v[126:127]
	v_cvt_pk_bf16_f32 v0, v0, v1
	v_cvt_pk_bf16_f32 v1, v2, v3
	global_store_dwordx2 v[68:69], v[0:1], off offset:1024
	s_nop 0
	v_pk_mul_f32 v[0:1], v[12:13], v[128:129]
	v_pk_add_f32 v[4:5], v[132:133], 1.0 op_sel_hi:[1, 0]
	v_pk_mul_f32 v[2:3], v[14:15], v[130:131]
	v_pk_add_f32 v[6:7], v[134:135], 1.0 op_sel_hi:[1, 0]
	v_pk_fma_f32 v[0:1], v[0:1], v[4:5], v[136:137]
	v_pk_fma_f32 v[2:3], v[2:3], v[6:7], v[138:139]
	v_cvt_pk_bf16_f32 v0, v0, v1
	v_cvt_pk_bf16_f32 v1, v2, v3
	global_store_dwordx2 v[68:69], v[0:1], off offset:1536
	s_cbranch_vccnz .LBB0_2181
	s_cmp_eq_u64 s[44:45], 0
	s_cbranch_scc1 .LBB0_2180
	global_store_dwordx4 v42, v[16:19], s[44:45]
	global_store_dwordx4 v42, v[20:23], s[44:45] offset:1024
	global_store_dwordx4 v42, v[24:27], s[44:45] offset:2048
	global_store_dwordx4 v42, v[28:31], s[44:45] offset:3072
	s_branch .LBB0_2180

; __device__ __forceinline__ float siluf_(float x) { return x / (1.f + __expf(-x)); }
; __global__ void __launch_bounds__(NTHR, 2) mk_fwd(Args args) {
;     ...
;                 for (int idx = tid; idx < 3072; idx += NTHR) { const int r = idx >> 10, k = idx & 1023; const float cv = (r < 2) ? ap->in[I_C][r * 1024 + k] : ap->in[I_CCTX][k]; sv[idx] = siluf_(cv); }
;                 __syncthreads();
;                 const int kq = tid >> 7, nn = tid & 127; float a0 = 0.f, a1 = 0.f, a2 = 0.f;
;                 const float* wp = ap->in[I_WMOD] + ((size_t)l * 1024 + kq * 256) * 6144 + n0 + nn;
; #pragma unroll 32
;                 for (int k = 0; k < 256; ++k) { const float w = wp[(size_t)k * 6144]; a0 += sv[kq * 256 + k] * w; a1 += sv[1024 + kq * 256 + k] * w; a2 += sv[2048 + kq * 256 + k] * w; }
.LBB0_2232:
	v_lshl_add_u64 v[190:191], v[70:71], 0, s[10:11]
	global_load_dword v102, v[190:191], off
	v_add_co_u32_e32 v190, vcc, 0x6000, v190
	s_nop 1
	v_addc_co_u32_e32 v191, vcc, 0, v191, vcc
	global_load_dword v103, v[190:191], off
	v_add_co_u32_e32 v190, vcc, 0x6000, v190
	s_nop 1
	v_addc_co_u32_e32 v191, vcc, 0, v191, vcc
	global_load_dword v104, v[190:191], off
	v_add_co_u32_e32 v190, vcc, 0x6000, v190
	s_nop 1
	v_addc_co_u32_e32 v191, vcc, 0, v191, vcc
	global_load_dword v105, v[190:191], off
	v_add_co_u32_e32 v190, vcc, 0x6000, v190
	s_nop 1
	v_addc_co_u32_e32 v191, vcc, 0, v191, vcc
	global_load_dword v106, v[190:191], off
	v_add_co_u32_e32 v190, vcc, 0x6000, v190
	s_nop 1
	v_addc_co_u32_e32 v191, vcc, 0, v191, vcc
	global_load_dword v107, v[190:191], off
	v_add_co_u32_e32 v190, vcc, 0x6000, v190
	s_nop 1
	v_addc_co_u32_e32 v191, vcc, 0, v191, vcc
	global_load_dword v108, v[190:191], off
	v_add_co_u32_e32 v190, vcc, 0x6000, v190
	s_nop 1
	v_addc_co_u32_e32 v191, vcc, 0, v191, vcc
	global_load_dword v109, v[190:191], off
	v_add_co_u32_e32 v190, vcc, 0x6000, v190
	s_nop 1
	v_addc_co_u32_e32 v191, vcc, 0, v191, vcc
	global_load_dword v110, v[190:191], off
	v_add_co_u32_e32 v190, vcc, 0x6000, v190
	s_nop 1
	v_addc_co_u32_e32 v191, vcc, 0, v191, vcc
	global_load_dword v111, v[190:191], off
	v_add_co_u32_e32 v190, vcc, 0x6000, v190
	s_nop 1
	v_addc_co_u32_e32 v191, vcc, 0, v191, vcc
	global_load_dword v112, v[190:191], off
	v_add_co_u32_e32 v190, vcc, 0x6000, v190
	s_nop 1
	v_addc_co_u32_e32 v191, vcc, 0, v191, vcc
	global_load_dword v113, v[190:191], off
	v_add_co_u32_e32 v190, vcc, 0x6000, v190
	s_nop 1
	v_addc_co_u32_e32 v191, vcc, 0, v191, vcc
	global_load_dword v114, v[190:191], off
	v_add_co_u32_e32 v190, vcc, 0x6000, v190
	s_nop 1
	v_addc_co_u32_e32 v191, vcc, 0, v191, vcc
	global_load_dword v115, v[190:191], off
	v_add_co_u32_e32 v190, vcc, 0x6000, v190
	s_nop 1
	v_addc_co_u32_e32 v191, vcc, 0, v191, vcc
	global_load_dword v116, v[190:191], off
	v_add_co_u32_e32 v190, vcc, 0x6000, v190
	s_nop 1
	v_addc_co_u32_e32 v191, vcc, 0, v191, vcc
	global_load_dword v117, v[190:191], off
	v_add_co_u32_e32 v190, vcc, 0x6000, v190
	s_nop 1
	v_addc_co_u32_e32 v191, vcc, 0, v191, vcc
	global_load_dword v118, v[190:191], off
	v_add_co_u32_e32 v190, vcc, 0x6000, v190
	s_nop 1
	v_addc_co_u32_e32 v191, vcc, 0, v191, vcc
	global_load_dword v119, v[190:191], off
	v_add_co_u32_e32 v190, vcc, 0x6000, v190
	s_nop 1
	v_addc_co_u32_e32 v191, vcc, 0, v191, vcc
	global_load_dword v120, v[190:191], off
	v_add_co_u32_e32 v190, vcc, 0x6000, v190
	s_nop 1
	v_addc_co_u32_e32 v191, vcc, 0, v191, vcc
	global_load_dword v121, v[190:191], off
	v_add_co_u32_e32 v190, vcc, 0x6000, v190
	s_nop 1
	v_addc_co_u32_e32 v191, vcc, 0, v191, vcc
	global_load_dword v122, v[190:191], off
	v_add_co_u32_e32 v190, vcc, 0x6000, v190
	s_nop 1
	v_addc_co_u32_e32 v191, vcc, 0, v191, vcc
	global_load_dword v123, v[190:191], off
	v_add_co_u32_e32 v190, vcc, 0x6000, v190
	s_nop 1
	v_addc_co_u32_e32 v191, vcc, 0, v191, vcc
	global_load_dword v124, v[190:191], off
	v_add_co_u32_e32 v190, vcc, 0x6000, v190
	s_nop 1
	v_addc_co_u32_e32 v191, vcc, 0, v191, vcc
	global_load_dword v125, v[190:191], off
	v_add_co_u32_e32 v190, vcc, 0x6000, v190
	s_nop 1
	v_addc_co_u32_e32 v191, vcc, 0, v191, vcc
	global_load_dword v126, v[190:191], off
	v_add_co_u32_e32 v190, vcc, 0x6000, v190
	s_nop 1
	v_addc_co_u32_e32 v191, vcc, 0, v191, vcc
	global_load_dword v127, v[190:191], off
	v_add_co_u32_e32 v190, vcc, 0x6000, v190
	s_nop 1
	v_addc_co_u32_e32 v191, vcc, 0, v191, vcc
	global_load_dword v128, v[190:191], off
	v_add_co_u32_e32 v190, vcc, 0x6000, v190
	s_nop 1
	v_addc_co_u32_e32 v191, vcc, 0, v191, vcc
	global_load_dword v129, v[190:191], off
	v_add_co_u32_e32 v190, vcc, 0x6000, v190
	s_nop 1
	v_addc_co_u32_e32 v191, vcc, 0, v191, vcc
	global_load_dword v130, v[190:191], off
	v_add_co_u32_e32 v190, vcc, 0x6000, v190
	s_nop 1
	v_addc_co_u32_e32 v191, vcc, 0, v191, vcc
	global_load_dword v131, v[190:191], off
	v_add_co_u32_e32 v190, vcc, 0x6000, v190
	s_nop 1
	v_addc_co_u32_e32 v191, vcc, 0, v191, vcc
	global_load_dword v132, v[190:191], off
	v_add_co_u32_e32 v190, vcc, 0x6000, v190
	s_nop 1
	v_addc_co_u32_e32 v191, vcc, 0, v191, vcc
	global_load_dword v133, v[190:191], off
	s_add_u32 s10, s10, 0xc0000
	s_addc_u32 s11, s11, 0
	s_mov_b32 s1, 3
; __global__ void __launch_bounds__(NTHR, 2) mk_fwd(Args args) {
;     ...
;                 const int kq = tid >> 7, nn = tid & 127; float a0 = 0.f, a1 = 0.f, a2 = 0.f;
;                 const float* wp = ap->in[I_WMOD] + ((size_t)l * 1024 + kq * 256) * 6144 + n0 + nn;
; #pragma unroll 32
;                 for (int k = 0; k < 256; ++k) { const float w = wp[(size_t)k * 6144]; a0 += sv[kq * 256 + k] * w; a1 += sv[1024 + kq * 256 + k] * w; a2 += sv[2048 + kq * 256 + k] * w; }
.Lph0_loop:
	v_lshl_add_u64 v[190:191], v[70:71], 0, s[10:11]
	global_load_dword v134, v[190:191], off
	v_add_co_u32_e32 v190, vcc, 0x6000, v190
	s_nop 1
	v_addc_co_u32_e32 v191, vcc, 0, v191, vcc
	global_load_dword v135, v[190:191], off
	v_add_co_u32_e32 v190, vcc, 0x6000, v190
	s_nop 1
	v_addc_co_u32_e32 v191, vcc, 0, v191, vcc
	global_load_dword v136, v[190:191], off
	v_add_co_u32_e32 v190, vcc, 0x6000, v190
	s_nop 1
	v_addc_co_u32_e32 v191, vcc, 0, v191, vcc
	global_load_dword v137, v[190:191], off
	v_add_co_u32_e32 v190, vcc, 0x6000, v190
	s_nop 1
	v_addc_co_u32_e32 v191, vcc, 0, v191, vcc
	global_load_dword v138, v[190:191], off
	v_add_co_u32_e32 v190, vcc, 0x6000, v190
	s_nop 1
	v_addc_co_u32_e32 v191, vcc, 0, v191, vcc
	global_load_dword v139, v[190:191], off
	v_add_co_u32_e32 v190, vcc, 0x6000, v190
	s_nop 1
	v_addc_co_u32_e32 v191, vcc, 0, v191, vcc
	global_load_dword v140, v[190:191], off
	v_add_co_u32_e32 v190, vcc, 0x6000, v190
	s_nop 1
	v_addc_co_u32_e32 v191, vcc, 0, v191, vcc
	global_load_dword v141, v[190:191], off
	v_add_co_u32_e32 v190, vcc, 0x6000, v190
	s_nop 1
	v_addc_co_u32_e32 v191, vcc, 0, v191, vcc
	global_load_dword v142, v[190:191], off
	v_add_co_u32_e32 v190, vcc, 0x6000, v190
	s_nop 1
	v_addc_co_u32_e32 v191, vcc, 0, v191, vcc
	global_load_dword v143, v[190:191], off
	v_add_co_u32_e32 v190, vcc, 0x6000, v190
	s_nop 1
	v_addc_co_u32_e32 v191, vcc, 0, v191, vcc
	global_load_dword v144, v[190:191], off
	v_add_co_u32_e32 v190, vcc, 0x6000, v190
	s_nop 1
	v_addc_co_u32_e32 v191, vcc, 0, v191, vcc
	global_load_dword v145, v[190:191], off
	v_add_co_u32_e32 v190, vcc, 0x6000, v190
	s_nop 1
	v_addc_co_u32_e32 v191, vcc, 0, v191, vcc
	global_load_dword v146, v[190:191], off
	v_add_co_u32_e32 v190, vcc, 0x6000, v190
	s_nop 1
	v_addc_co_u32_e32 v191, vcc, 0, v191, vcc
	global_load_dword v147, v[190:191], off
	v_add_co_u32_e32 v190, vcc, 0x6000, v190
	s_nop 1
	v_addc_co_u32_e32 v191, vcc, 0, v191, vcc
	global_load_dword v148, v[190:191], off
	v_add_co_u32_e32 v190, vcc, 0x6000, v190
	s_nop 1
	v_addc_co_u32_e32 v191, vcc, 0, v191, vcc
	global_load_dword v149, v[190:191], off
	v_add_co_u32_e32 v190, vcc, 0x6000, v190
	s_nop 1
	v_addc_co_u32_e32 v191, vcc, 0, v191, vcc
	global_load_dword v150, v[190:191], off
	v_add_co_u32_e32 v190, vcc, 0x6000, v190
	s_nop 1
	v_addc_co_u32_e32 v191, vcc, 0, v191, vcc
	global_load_dword v151, v[190:191], off
	v_add_co_u32_e32 v190, vcc, 0x6000, v190
	s_nop 1
	v_addc_co_u32_e32 v191, vcc, 0, v191, vcc
	global_load_dword v152, v[190:191], off
	v_add_co_u32_e32 v190, vcc, 0x6000, v190
	s_nop 1
	v_addc_co_u32_e32 v191, vcc, 0, v191, vcc
	global_load_dword v153, v[190:191], off
	v_add_co_u32_e32 v190, vcc, 0x6000, v190
	s_nop 1
	v_addc_co_u32_e32 v191, vcc, 0, v191, vcc
	global_load_dword v154, v[190:191], off
	v_add_co_u32_e32 v190, vcc, 0x6000, v190
	s_nop 1
	v_addc_co_u32_e32 v191, vcc, 0, v191, vcc
	global_load_dword v155, v[190:191], off
	v_add_co_u32_e32 v190, vcc, 0x6000, v190
	s_nop 1
	v_addc_co_u32_e32 v191, vcc, 0, v191, vcc
	global_load_dword v156, v[190:191], off
	v_add_co_u32_e32 v190, vcc, 0x6000, v190
	s_nop 1
	v_addc_co_u32_e32 v191, vcc, 0, v191, vcc
	global_load_dword v157, v[190:191], off
	v_add_co_u32_e32 v190, vcc, 0x6000, v190
	s_nop 1
	v_addc_co_u32_e32 v191, vcc, 0, v191, vcc
	global_load_dword v158, v[190:191], off
	v_add_co_u32_e32 v190, vcc, 0x6000, v190
	s_nop 1
	v_addc_co_u32_e32 v191, vcc, 0, v191, vcc
	global_load_dword v159, v[190:191], off
	v_add_co_u32_e32 v190, vcc, 0x6000, v190
	s_nop 1
	v_addc_co_u32_e32 v191, vcc, 0, v191, vcc
	global_load_dword v160, v[190:191], off
	v_add_co_u32_e32 v190, vcc, 0x6000, v190
	s_nop 1
	v_addc_co_u32_e32 v191, vcc, 0, v191, vcc
	global_load_dword v161, v[190:191], off
	v_add_co_u32_e32 v190, vcc, 0x6000, v190
	s_nop 1
	v_addc_co_u32_e32 v191, vcc, 0, v191, vcc
	global_load_dword v162, v[190:191], off
	v_add_co_u32_e32 v190, vcc, 0x6000, v190
	s_nop 1
	v_addc_co_u32_e32 v191, vcc, 0, v191, vcc
	global_load_dword v163, v[190:191], off
	v_add_co_u32_e32 v190, vcc, 0x6000, v190
	s_nop 1
	v_addc_co_u32_e32 v191, vcc, 0, v191, vcc
	global_load_dword v164, v[190:191], off
	v_add_co_u32_e32 v190, vcc, 0x6000, v190
	s_nop 1
	v_addc_co_u32_e32 v191, vcc, 0, v191, vcc
	global_load_dword v165, v[190:191], off
	s_add_u32 s10, s10, 0xc0000
	s_addc_u32 s11, s11, 0
	ds_read_b128 v[166:169], v65 offset:0
	ds_read_b128 v[170:173], v65 offset:16
	ds_read_b128 v[174:177], v65 offset:4096
	ds_read_b128 v[178:181], v65 offset:4112
	ds_read_b128 v[182:185], v65 offset:8192
	ds_read_b128 v[186:189], v65 offset:8208
	s_waitcnt lgkmcnt(0)
	s_waitcnt vmcnt(63)
	v_fmac_f32_e32 v28, v102, v166
	v_fmac_f32_e32 v29, v102, v174
	v_fmac_f32_e32 v43, v102, v182
	s_waitcnt vmcnt(62)
	v_fmac_f32_e32 v28, v103, v167
	v_fmac_f32_e32 v29, v103, v175
	v_fmac_f32_e32 v43, v103, v183
	s_waitcnt vmcnt(61)
	v_fmac_f32_e32 v28, v104, v168
	v_fmac_f32_e32 v29, v104, v176
	v_fmac_f32_e32 v43, v104, v184
	s_waitcnt vmcnt(60)
	v_fmac_f32_e32 v28, v105, v169
	v_fmac_f32_e32 v29, v105, v177
	v_fmac_f32_e32 v43, v105, v185
	s_waitcnt vmcnt(59)
	v_fmac_f32_e32 v28, v106, v170
	v_fmac_f32_e32 v29, v106, v178
	v_fmac_f32_e32 v43, v106, v186
	s_waitcnt vmcnt(58)
	v_fmac_f32_e32 v28, v107, v171
	v_fmac_f32_e32 v29, v107, v179
	v_fmac_f32_e32 v43, v107, v187
	s_waitcnt vmcnt(57)
	v_fmac_f32_e32 v28, v108, v172
	v_fmac_f32_e32 v29, v108, v180
	v_fmac_f32_e32 v43, v108, v188
	s_waitcnt vmcnt(56)
	v_fmac_f32_e32 v28, v109, v173
	v_fmac_f32_e32 v29, v109, v181
	v_fmac_f32_e32 v43, v109, v189
	ds_read_b128 v[166:169], v65 offset:32
	ds_read_b128 v[170:173], v65 offset:48
	ds_read_b128 v[174:177], v65 offset:4128
	ds_read_b128 v[178:181], v65 offset:4144
	ds_read_b128 v[182:185], v65 offset:8224
	ds_read_b128 v[186:189], v65 offset:8240
	s_waitcnt lgkmcnt(0)
; __global__ void __launch_bounds__(NTHR, 2) mk_fwd(Args args) {
;     ...
; #pragma unroll 32
;                 for (int k = 0; k < 256; ++k) { const float w = wp[(size_t)k * 6144]; a0 += sv[kq * 256 + k] * w; a1 += sv[1024 + kq * 256 + k] * w; a2 += sv[2048 + kq * 256 + k] * w; }
	s_waitcnt vmcnt(55)
	v_fmac_f32_e32 v28, v110, v166
	v_fmac_f32_e32 v29, v110, v174
	v_fmac_f32_e32 v43, v110, v182
	s_waitcnt vmcnt(54)
	v_fmac_f32_e32 v28, v111, v167
	v_fmac_f32_e32 v29, v111, v175
	v_fmac_f32_e32 v43, v111, v183
	s_waitcnt vmcnt(53)
	v_fmac_f32_e32 v28, v112, v168
	v_fmac_f32_e32 v29, v112, v176
	v_fmac_f32_e32 v43, v112, v184
	s_waitcnt vmcnt(52)
	v_fmac_f32_e32 v28, v113, v169
	v_fmac_f32_e32 v29, v113, v177
	v_fmac_f32_e32 v43, v113, v185
	s_waitcnt vmcnt(51)
	v_fmac_f32_e32 v28, v114, v170
	v_fmac_f32_e32 v29, v114, v178
	v_fmac_f32_e32 v43, v114, v186
	s_waitcnt vmcnt(50)
	v_fmac_f32_e32 v28, v115, v171
	v_fmac_f32_e32 v29, v115, v179
	v_fmac_f32_e32 v43, v115, v187
	s_waitcnt vmcnt(49)
	v_fmac_f32_e32 v28, v116, v172
	v_fmac_f32_e32 v29, v116, v180
	v_fmac_f32_e32 v43, v116, v188
	s_waitcnt vmcnt(48)
	v_fmac_f32_e32 v28, v117, v173
	v_fmac_f32_e32 v29, v117, v181
	v_fmac_f32_e32 v43, v117, v189
	ds_read_b128 v[166:169], v65 offset:64
	ds_read_b128 v[170:173], v65 offset:80
	ds_read_b128 v[174:177], v65 offset:4160
	ds_read_b128 v[178:181], v65 offset:4176
	ds_read_b128 v[182:185], v65 offset:8256
	ds_read_b128 v[186:189], v65 offset:8272
	s_waitcnt lgkmcnt(0)
	s_waitcnt vmcnt(47)
	v_fmac_f32_e32 v28, v118, v166
	v_fmac_f32_e32 v29, v118, v174
	v_fmac_f32_e32 v43, v118, v182
	s_waitcnt vmcnt(46)
	v_fmac_f32_e32 v28, v119, v167
	v_fmac_f32_e32 v29, v119, v175
	v_fmac_f32_e32 v43, v119, v183
	s_waitcnt vmcnt(45)
	v_fmac_f32_e32 v28, v120, v168
	v_fmac_f32_e32 v29, v120, v176
	v_fmac_f32_e32 v43, v120, v184
	s_waitcnt vmcnt(44)
	v_fmac_f32_e32 v28, v121, v169
	v_fmac_f32_e32 v29, v121, v177
	v_fmac_f32_e32 v43, v121, v185
	s_waitcnt vmcnt(43)
	v_fmac_f32_e32 v28, v122, v170
	v_fmac_f32_e32 v29, v122, v178
	v_fmac_f32_e32 v43, v122, v186
	s_waitcnt vmcnt(42)
	v_fmac_f32_e32 v28, v123, v171
	v_fmac_f32_e32 v29, v123, v179
	v_fmac_f32_e32 v43, v123, v187
	s_waitcnt vmcnt(41)
	v_fmac_f32_e32 v28, v124, v172
	v_fmac_f32_e32 v29, v124, v180
	v_fmac_f32_e32 v43, v124, v188
	s_waitcnt vmcnt(40)
	v_fmac_f32_e32 v28, v125, v173
	v_fmac_f32_e32 v29, v125, v181
	v_fmac_f32_e32 v43, v125, v189
	ds_read_b128 v[166:169], v65 offset:96
	ds_read_b128 v[170:173], v65 offset:112
	ds_read_b128 v[174:177], v65 offset:4192
	ds_read_b128 v[178:181], v65 offset:4208
	ds_read_b128 v[182:185], v65 offset:8288
	ds_read_b128 v[186:189], v65 offset:8304
	s_waitcnt lgkmcnt(0)
	s_waitcnt vmcnt(39)
	v_fmac_f32_e32 v28, v126, v166
	v_fmac_f32_e32 v29, v126, v174
	v_fmac_f32_e32 v43, v126, v182
	s_waitcnt vmcnt(38)
	v_fmac_f32_e32 v28, v127, v167
	v_fmac_f32_e32 v29, v127, v175
	v_fmac_f32_e32 v43, v127, v183
	s_waitcnt vmcnt(37)
	v_fmac_f32_e32 v28, v128, v168
	v_fmac_f32_e32 v29, v128, v176
	v_fmac_f32_e32 v43, v128, v184
	s_waitcnt vmcnt(36)
	v_fmac_f32_e32 v28, v129, v169
	v_fmac_f32_e32 v29, v129, v177
	v_fmac_f32_e32 v43, v129, v185
	s_waitcnt vmcnt(35)
	v_fmac_f32_e32 v28, v130, v170
	v_fmac_f32_e32 v29, v130, v178
	v_fmac_f32_e32 v43, v130, v186
	s_waitcnt vmcnt(34)
	v_fmac_f32_e32 v28, v131, v171
	v_fmac_f32_e32 v29, v131, v179
	v_fmac_f32_e32 v43, v131, v187
	s_waitcnt vmcnt(33)
	v_fmac_f32_e32 v28, v132, v172
	v_fmac_f32_e32 v29, v132, v180
	v_fmac_f32_e32 v43, v132, v188
	s_waitcnt vmcnt(32)
	v_fmac_f32_e32 v28, v133, v173
	v_fmac_f32_e32 v29, v133, v181
	v_fmac_f32_e32 v43, v133, v189
	v_add_u32_e32 v65, 0x80, v65
	v_lshl_add_u64 v[190:191], v[70:71], 0, s[10:11]
	global_load_dword v102, v[190:191], off
	v_add_co_u32_e32 v190, vcc, 0x6000, v190
	s_nop 1
	v_addc_co_u32_e32 v191, vcc, 0, v191, vcc
	global_load_dword v103, v[190:191], off
	v_add_co_u32_e32 v190, vcc, 0x6000, v190
	s_nop 1
	v_addc_co_u32_e32 v191, vcc, 0, v191, vcc
	global_load_dword v104, v[190:191], off
	v_add_co_u32_e32 v190, vcc, 0x6000, v190
	s_nop 1
	v_addc_co_u32_e32 v191, vcc, 0, v191, vcc
	global_load_dword v105, v[190:191], off
	v_add_co_u32_e32 v190, vcc, 0x6000, v190
	s_nop 1
	v_addc_co_u32_e32 v191, vcc, 0, v191, vcc
	global_load_dword v106, v[190:191], off
	v_add_co_u32_e32 v190, vcc, 0x6000, v190
	s_nop 1
	v_addc_co_u32_e32 v191, vcc, 0, v191, vcc
	global_load_dword v107, v[190:191], off
	v_add_co_u32_e32 v190, vcc, 0x6000, v190
	s_nop 1
	v_addc_co_u32_e32 v191, vcc, 0, v191, vcc
	global_load_dword v108, v[190:191], off
	v_add_co_u32_e32 v190, vcc, 0x6000, v190
	s_nop 1
	v_addc_co_u32_e32 v191, vcc, 0, v191, vcc
	global_load_dword v109, v[190:191], off
	v_add_co_u32_e32 v190, vcc, 0x6000, v190
	s_nop 1
	v_addc_co_u32_e32 v191, vcc, 0, v191, vcc
	global_load_dword v110, v[190:191], off
	v_add_co_u32_e32 v190, vcc, 0x6000, v190
	s_nop 1
	v_addc_co_u32_e32 v191, vcc, 0, v191, vcc
	global_load_dword v111, v[190:191], off
	v_add_co_u32_e32 v190, vcc, 0x6000, v190
	s_nop 1
	v_addc_co_u32_e32 v191, vcc, 0, v191, vcc
	global_load_dword v112, v[190:191], off
	v_add_co_u32_e32 v190, vcc, 0x6000, v190
	s_nop 1
	v_addc_co_u32_e32 v191, vcc, 0, v191, vcc
	global_load_dword v113, v[190:191], off
	v_add_co_u32_e32 v190, vcc, 0x6000, v190
	s_nop 1
	v_addc_co_u32_e32 v191, vcc, 0, v191, vcc
	global_load_dword v114, v[190:191], off
	v_add_co_u32_e32 v190, vcc, 0x6000, v190
	s_nop 1
	v_addc_co_u32_e32 v191, vcc, 0, v191, vcc
	global_load_dword v115, v[190:191], off
	v_add_co_u32_e32 v190, vcc, 0x6000, v190
	s_nop 1
	v_addc_co_u32_e32 v191, vcc, 0, v191, vcc
	global_load_dword v116, v[190:191], off
	v_add_co_u32_e32 v190, vcc, 0x6000, v190
	s_nop 1
	v_addc_co_u32_e32 v191, vcc, 0, v191, vcc
	global_load_dword v117, v[190:191], off
	v_add_co_u32_e32 v190, vcc, 0x6000, v190
	s_nop 1
	v_addc_co_u32_e32 v191, vcc, 0, v191, vcc
	global_load_dword v118, v[190:191], off
; __global__ void __launch_bounds__(NTHR, 2) mk_fwd(Args args) {
;     ...
; #pragma unroll 32
;                 for (int k = 0; k < 256; ++k) { const float w = wp[(size_t)k * 6144]; a0 += sv[kq * 256 + k] * w; a1 += sv[1024 + kq * 256 + k] * w; a2 += sv[2048 + kq * 256 + k] * w; }
	v_add_co_u32_e32 v190, vcc, 0x6000, v190
	s_nop 1
	v_addc_co_u32_e32 v191, vcc, 0, v191, vcc
	global_load_dword v119, v[190:191], off
	v_add_co_u32_e32 v190, vcc, 0x6000, v190
	s_nop 1
	v_addc_co_u32_e32 v191, vcc, 0, v191, vcc
	global_load_dword v120, v[190:191], off
	v_add_co_u32_e32 v190, vcc, 0x6000, v190
	s_nop 1
	v_addc_co_u32_e32 v191, vcc, 0, v191, vcc
	global_load_dword v121, v[190:191], off
	v_add_co_u32_e32 v190, vcc, 0x6000, v190
	s_nop 1
	v_addc_co_u32_e32 v191, vcc, 0, v191, vcc
	global_load_dword v122, v[190:191], off
	v_add_co_u32_e32 v190, vcc, 0x6000, v190
	s_nop 1
	v_addc_co_u32_e32 v191, vcc, 0, v191, vcc
	global_load_dword v123, v[190:191], off
	v_add_co_u32_e32 v190, vcc, 0x6000, v190
	s_nop 1
	v_addc_co_u32_e32 v191, vcc, 0, v191, vcc
	global_load_dword v124, v[190:191], off
	v_add_co_u32_e32 v190, vcc, 0x6000, v190
	s_nop 1
	v_addc_co_u32_e32 v191, vcc, 0, v191, vcc
	global_load_dword v125, v[190:191], off
	v_add_co_u32_e32 v190, vcc, 0x6000, v190
	s_nop 1
	v_addc_co_u32_e32 v191, vcc, 0, v191, vcc
	global_load_dword v126, v[190:191], off
	v_add_co_u32_e32 v190, vcc, 0x6000, v190
	s_nop 1
	v_addc_co_u32_e32 v191, vcc, 0, v191, vcc
	global_load_dword v127, v[190:191], off
	v_add_co_u32_e32 v190, vcc, 0x6000, v190
	s_nop 1
	v_addc_co_u32_e32 v191, vcc, 0, v191, vcc
	global_load_dword v128, v[190:191], off
	v_add_co_u32_e32 v190, vcc, 0x6000, v190
	s_nop 1
	v_addc_co_u32_e32 v191, vcc, 0, v191, vcc
	global_load_dword v129, v[190:191], off
	v_add_co_u32_e32 v190, vcc, 0x6000, v190
	s_nop 1
	v_addc_co_u32_e32 v191, vcc, 0, v191, vcc
	global_load_dword v130, v[190:191], off
	v_add_co_u32_e32 v190, vcc, 0x6000, v190
	s_nop 1
	v_addc_co_u32_e32 v191, vcc, 0, v191, vcc
	global_load_dword v131, v[190:191], off
	v_add_co_u32_e32 v190, vcc, 0x6000, v190
	s_nop 1
	v_addc_co_u32_e32 v191, vcc, 0, v191, vcc
	global_load_dword v132, v[190:191], off
	v_add_co_u32_e32 v190, vcc, 0x6000, v190
	s_nop 1
	v_addc_co_u32_e32 v191, vcc, 0, v191, vcc
	global_load_dword v133, v[190:191], off
	s_add_u32 s10, s10, 0xc0000
	s_addc_u32 s11, s11, 0
	ds_read_b128 v[166:169], v65 offset:0
	ds_read_b128 v[170:173], v65 offset:16
	ds_read_b128 v[174:177], v65 offset:4096
	ds_read_b128 v[178:181], v65 offset:4112
	ds_read_b128 v[182:185], v65 offset:8192
	ds_read_b128 v[186:189], v65 offset:8208
	s_waitcnt lgkmcnt(0)
	s_waitcnt vmcnt(63)
	v_fmac_f32_e32 v28, v134, v166
	v_fmac_f32_e32 v29, v134, v174
	v_fmac_f32_e32 v43, v134, v182
	s_waitcnt vmcnt(62)
	v_fmac_f32_e32 v28, v135, v167
	v_fmac_f32_e32 v29, v135, v175
	v_fmac_f32_e32 v43, v135, v183
	s_waitcnt vmcnt(61)
	v_fmac_f32_e32 v28, v136, v168
	v_fmac_f32_e32 v29, v136, v176
	v_fmac_f32_e32 v43, v136, v184
	s_waitcnt vmcnt(60)
	v_fmac_f32_e32 v28, v137, v169
	v_fmac_f32_e32 v29, v137, v177
	v_fmac_f32_e32 v43, v137, v185
	s_waitcnt vmcnt(59)
	v_fmac_f32_e32 v28, v138, v170
	v_fmac_f32_e32 v29, v138, v178
	v_fmac_f32_e32 v43, v138, v186
	s_waitcnt vmcnt(58)
	v_fmac_f32_e32 v28, v139, v171
	v_fmac_f32_e32 v29, v139, v179
	v_fmac_f32_e32 v43, v139, v187
	s_waitcnt vmcnt(57)
	v_fmac_f32_e32 v28, v140, v172
	v_fmac_f32_e32 v29, v140, v180
	v_fmac_f32_e32 v43, v140, v188
	s_waitcnt vmcnt(56)
	v_fmac_f32_e32 v28, v141, v173
	v_fmac_f32_e32 v29, v141, v181
	v_fmac_f32_e32 v43, v141, v189
	ds_read_b128 v[166:169], v65 offset:32
	ds_read_b128 v[170:173], v65 offset:48
	ds_read_b128 v[174:177], v65 offset:4128
	ds_read_b128 v[178:181], v65 offset:4144
	ds_read_b128 v[182:185], v65 offset:8224
	ds_read_b128 v[186:189], v65 offset:8240
	s_waitcnt lgkmcnt(0)
	s_waitcnt vmcnt(55)
	v_fmac_f32_e32 v28, v142, v166
	v_fmac_f32_e32 v29, v142, v174
	v_fmac_f32_e32 v43, v142, v182
	s_waitcnt vmcnt(54)
	v_fmac_f32_e32 v28, v143, v167
	v_fmac_f32_e32 v29, v143, v175
	v_fmac_f32_e32 v43, v143, v183
	s_waitcnt vmcnt(53)
	v_fmac_f32_e32 v28, v144, v168
	v_fmac_f32_e32 v29, v144, v176
	v_fmac_f32_e32 v43, v144, v184
	s_waitcnt vmcnt(52)
	v_fmac_f32_e32 v28, v145, v169
	v_fmac_f32_e32 v29, v145, v177
	v_fmac_f32_e32 v43, v145, v185
	s_waitcnt vmcnt(51)
	v_fmac_f32_e32 v28, v146, v170
	v_fmac_f32_e32 v29, v146, v178
	v_fmac_f32_e32 v43, v146, v186
	s_waitcnt vmcnt(50)
	v_fmac_f32_e32 v28, v147, v171
	v_fmac_f32_e32 v29, v147, v179
	v_fmac_f32_e32 v43, v147, v187
	s_waitcnt vmcnt(49)
	v_fmac_f32_e32 v28, v148, v172
	v_fmac_f32_e32 v29, v148, v180
	v_fmac_f32_e32 v43, v148, v188
	s_waitcnt vmcnt(48)
	v_fmac_f32_e32 v28, v149, v173
	v_fmac_f32_e32 v29, v149, v181
	v_fmac_f32_e32 v43, v149, v189
	ds_read_b128 v[166:169], v65 offset:64
	ds_read_b128 v[170:173], v65 offset:80
	ds_read_b128 v[174:177], v65 offset:4160
	ds_read_b128 v[178:181], v65 offset:4176
	ds_read_b128 v[182:185], v65 offset:8256
	ds_read_b128 v[186:189], v65 offset:8272
	s_waitcnt lgkmcnt(0)
	s_waitcnt vmcnt(47)
	v_fmac_f32_e32 v28, v150, v166
	v_fmac_f32_e32 v29, v150, v174
	v_fmac_f32_e32 v43, v150, v182
	s_waitcnt vmcnt(46)
	v_fmac_f32_e32 v28, v151, v167
	v_fmac_f32_e32 v29, v151, v175
	v_fmac_f32_e32 v43, v151, v183
	s_waitcnt vmcnt(45)
	v_fmac_f32_e32 v28, v152, v168
	v_fmac_f32_e32 v29, v152, v176
	v_fmac_f32_e32 v43, v152, v184
	s_waitcnt vmcnt(44)
	v_fmac_f32_e32 v28, v153, v169
	v_fmac_f32_e32 v29, v153, v177
	v_fmac_f32_e32 v43, v153, v185
	s_waitcnt vmcnt(43)
	v_fmac_f32_e32 v28, v154, v170
	v_fmac_f32_e32 v29, v154, v178
	v_fmac_f32_e32 v43, v154, v186
	s_waitcnt vmcnt(42)
	v_fmac_f32_e32 v28, v155, v171
	v_fmac_f32_e32 v29, v155, v179
	v_fmac_f32_e32 v43, v155, v187
	s_waitcnt vmcnt(41)
	v_fmac_f32_e32 v28, v156, v172
	v_fmac_f32_e32 v29, v156, v180
	v_fmac_f32_e32 v43, v156, v188
	s_waitcnt vmcnt(40)
	v_fmac_f32_e32 v28, v157, v173
	v_fmac_f32_e32 v29, v157, v181
	v_fmac_f32_e32 v43, v157, v189
	ds_read_b128 v[166:169], v65 offset:96
	ds_read_b128 v[170:173], v65 offset:112
	ds_read_b128 v[174:177], v65 offset:4192
	ds_read_b128 v[178:181], v65 offset:4208
	ds_read_b128 v[182:185], v65 offset:8288
	ds_read_b128 v[186:189], v65 offset:8304
	s_waitcnt lgkmcnt(0)
	s_waitcnt vmcnt(39)
	v_fmac_f32_e32 v28, v158, v166
	v_fmac_f32_e32 v29, v158, v174
	v_fmac_f32_e32 v43, v158, v182
	s_waitcnt vmcnt(38)
	v_fmac_f32_e32 v28, v159, v167
	v_fmac_f32_e32 v29, v159, v175
	v_fmac_f32_e32 v43, v159, v183
	s_waitcnt vmcnt(37)
	v_fmac_f32_e32 v28, v160, v168
	v_fmac_f32_e32 v29, v160, v176
	v_fmac_f32_e32 v43, v160, v184
	s_waitcnt vmcnt(36)
	v_fmac_f32_e32 v28, v161, v169
	v_fmac_f32_e32 v29, v161, v177
	v_fmac_f32_e32 v43, v161, v185
	s_waitcnt vmcnt(35)
	v_fmac_f32_e32 v28, v162, v170
	v_fmac_f32_e32 v29, v162, v178
	v_fmac_f32_e32 v43, v162, v186
	s_waitcnt vmcnt(34)
	v_fmac_f32_e32 v28, v163, v171
	v_fmac_f32_e32 v29, v163, v179
	v_fmac_f32_e32 v43, v163, v187
	s_waitcnt vmcnt(33)
	v_fmac_f32_e32 v28, v164, v172
	v_fmac_f32_e32 v29, v164, v180
	v_fmac_f32_e32 v43, v164, v188
	s_waitcnt vmcnt(32)
	v_fmac_f32_e32 v28, v165, v173
	v_fmac_f32_e32 v29, v165, v181
	v_fmac_f32_e32 v43, v165, v189
	v_add_u32_e32 v65, 0x80, v65
	s_sub_i32 s1, s1, 1
	s_cmp_lg_u32 s1, 0
	s_cbranch_scc1 .Lph0_loop
; __global__ void __launch_bounds__(NTHR, 2) mk_fwd(Args args) {
;     ...
; #pragma unroll 32
;                 for (int k = 0; k < 256; ++k) { const float w = wp[(size_t)k * 6144]; a0 += sv[kq * 256 + k] * w; a1 += sv[1024 + kq * 256 + k] * w; a2 += sv[2048 + kq * 256 + k] * w; }
	v_lshl_add_u64 v[190:191], v[70:71], 0, s[10:11]
	global_load_dword v134, v[190:191], off
	v_add_co_u32_e32 v190, vcc, 0x6000, v190
	s_nop 1
	v_addc_co_u32_e32 v191, vcc, 0, v191, vcc
	global_load_dword v135, v[190:191], off
	v_add_co_u32_e32 v190, vcc, 0x6000, v190
	s_nop 1
	v_addc_co_u32_e32 v191, vcc, 0, v191, vcc
	global_load_dword v136, v[190:191], off
	v_add_co_u32_e32 v190, vcc, 0x6000, v190
	s_nop 1
	v_addc_co_u32_e32 v191, vcc, 0, v191, vcc
	global_load_dword v137, v[190:191], off
	v_add_co_u32_e32 v190, vcc, 0x6000, v190
	s_nop 1
	v_addc_co_u32_e32 v191, vcc, 0, v191, vcc
	global_load_dword v138, v[190:191], off
	v_add_co_u32_e32 v190, vcc, 0x6000, v190
	s_nop 1
	v_addc_co_u32_e32 v191, vcc, 0, v191, vcc
	global_load_dword v139, v[190:191], off
	v_add_co_u32_e32 v190, vcc, 0x6000, v190
	s_nop 1
	v_addc_co_u32_e32 v191, vcc, 0, v191, vcc
	global_load_dword v140, v[190:191], off
	v_add_co_u32_e32 v190, vcc, 0x6000, v190
	s_nop 1
	v_addc_co_u32_e32 v191, vcc, 0, v191, vcc
	global_load_dword v141, v[190:191], off
	v_add_co_u32_e32 v190, vcc, 0x6000, v190
	s_nop 1
	v_addc_co_u32_e32 v191, vcc, 0, v191, vcc
	global_load_dword v142, v[190:191], off
	v_add_co_u32_e32 v190, vcc, 0x6000, v190
	s_nop 1
	v_addc_co_u32_e32 v191, vcc, 0, v191, vcc
	global_load_dword v143, v[190:191], off
	v_add_co_u32_e32 v190, vcc, 0x6000, v190
	s_nop 1
	v_addc_co_u32_e32 v191, vcc, 0, v191, vcc
	global_load_dword v144, v[190:191], off
	v_add_co_u32_e32 v190, vcc, 0x6000, v190
	s_nop 1
	v_addc_co_u32_e32 v191, vcc, 0, v191, vcc
	global_load_dword v145, v[190:191], off
	v_add_co_u32_e32 v190, vcc, 0x6000, v190
	s_nop 1
	v_addc_co_u32_e32 v191, vcc, 0, v191, vcc
	global_load_dword v146, v[190:191], off
	v_add_co_u32_e32 v190, vcc, 0x6000, v190
	s_nop 1
	v_addc_co_u32_e32 v191, vcc, 0, v191, vcc
	global_load_dword v147, v[190:191], off
	v_add_co_u32_e32 v190, vcc, 0x6000, v190
	s_nop 1
	v_addc_co_u32_e32 v191, vcc, 0, v191, vcc
	global_load_dword v148, v[190:191], off
	v_add_co_u32_e32 v190, vcc, 0x6000, v190
	s_nop 1
	v_addc_co_u32_e32 v191, vcc, 0, v191, vcc
	global_load_dword v149, v[190:191], off
	v_add_co_u32_e32 v190, vcc, 0x6000, v190
	s_nop 1
	v_addc_co_u32_e32 v191, vcc, 0, v191, vcc
	global_load_dword v150, v[190:191], off
	v_add_co_u32_e32 v190, vcc, 0x6000, v190
	s_nop 1
	v_addc_co_u32_e32 v191, vcc, 0, v191, vcc
	global_load_dword v151, v[190:191], off
	v_add_co_u32_e32 v190, vcc, 0x6000, v190
	s_nop 1
	v_addc_co_u32_e32 v191, vcc, 0, v191, vcc
	global_load_dword v152, v[190:191], off
	v_add_co_u32_e32 v190, vcc, 0x6000, v190
	s_nop 1
	v_addc_co_u32_e32 v191, vcc, 0, v191, vcc
	global_load_dword v153, v[190:191], off
	v_add_co_u32_e32 v190, vcc, 0x6000, v190
	s_nop 1
	v_addc_co_u32_e32 v191, vcc, 0, v191, vcc
	global_load_dword v154, v[190:191], off
	v_add_co_u32_e32 v190, vcc, 0x6000, v190
	s_nop 1
	v_addc_co_u32_e32 v191, vcc, 0, v191, vcc
	global_load_dword v155, v[190:191], off
	v_add_co_u32_e32 v190, vcc, 0x6000, v190
	s_nop 1
	v_addc_co_u32_e32 v191, vcc, 0, v191, vcc
	global_load_dword v156, v[190:191], off
	v_add_co_u32_e32 v190, vcc, 0x6000, v190
	s_nop 1
	v_addc_co_u32_e32 v191, vcc, 0, v191, vcc
	global_load_dword v157, v[190:191], off
	v_add_co_u32_e32 v190, vcc, 0x6000, v190
	s_nop 1
	v_addc_co_u32_e32 v191, vcc, 0, v191, vcc
	global_load_dword v158, v[190:191], off
	v_add_co_u32_e32 v190, vcc, 0x6000, v190
	s_nop 1
	v_addc_co_u32_e32 v191, vcc, 0, v191, vcc
	global_load_dword v159, v[190:191], off
	v_add_co_u32_e32 v190, vcc, 0x6000, v190
	s_nop 1
	v_addc_co_u32_e32 v191, vcc, 0, v191, vcc
	global_load_dword v160, v[190:191], off
	v_add_co_u32_e32 v190, vcc, 0x6000, v190
	s_nop 1
	v_addc_co_u32_e32 v191, vcc, 0, v191, vcc
	global_load_dword v161, v[190:191], off
	v_add_co_u32_e32 v190, vcc, 0x6000, v190
	s_nop 1
	v_addc_co_u32_e32 v191, vcc, 0, v191, vcc
	global_load_dword v162, v[190:191], off
	v_add_co_u32_e32 v190, vcc, 0x6000, v190
	s_nop 1
	v_addc_co_u32_e32 v191, vcc, 0, v191, vcc
	global_load_dword v163, v[190:191], off
	v_add_co_u32_e32 v190, vcc, 0x6000, v190
	s_nop 1
	v_addc_co_u32_e32 v191, vcc, 0, v191, vcc
	global_load_dword v164, v[190:191], off
	v_add_co_u32_e32 v190, vcc, 0x6000, v190
	s_nop 1
	v_addc_co_u32_e32 v191, vcc, 0, v191, vcc
	global_load_dword v165, v[190:191], off
	s_add_u32 s10, s10, 0xc0000
	s_addc_u32 s11, s11, 0
	ds_read_b128 v[166:169], v65 offset:0
	ds_read_b128 v[170:173], v65 offset:16
	ds_read_b128 v[174:177], v65 offset:4096
	ds_read_b128 v[178:181], v65 offset:4112
	ds_read_b128 v[182:185], v65 offset:8192
	ds_read_b128 v[186:189], v65 offset:8208
	s_waitcnt lgkmcnt(0)
	s_waitcnt vmcnt(63)
	v_fmac_f32_e32 v28, v102, v166
	v_fmac_f32_e32 v29, v102, v174
	v_fmac_f32_e32 v43, v102, v182
	s_waitcnt vmcnt(62)
	v_fmac_f32_e32 v28, v103, v167
	v_fmac_f32_e32 v29, v103, v175
	v_fmac_f32_e32 v43, v103, v183
	s_waitcnt vmcnt(61)
	v_fmac_f32_e32 v28, v104, v168
	v_fmac_f32_e32 v29, v104, v176
	v_fmac_f32_e32 v43, v104, v184
	s_waitcnt vmcnt(60)
	v_fmac_f32_e32 v28, v105, v169
	v_fmac_f32_e32 v29, v105, v177
	v_fmac_f32_e32 v43, v105, v185
	s_waitcnt vmcnt(59)
	v_fmac_f32_e32 v28, v106, v170
	v_fmac_f32_e32 v29, v106, v178
	v_fmac_f32_e32 v43, v106, v186
	s_waitcnt vmcnt(58)
	v_fmac_f32_e32 v28, v107, v171
	v_fmac_f32_e32 v29, v107, v179
	v_fmac_f32_e32 v43, v107, v187
	s_waitcnt vmcnt(57)
	v_fmac_f32_e32 v28, v108, v172
	v_fmac_f32_e32 v29, v108, v180
	v_fmac_f32_e32 v43, v108, v188
	s_waitcnt vmcnt(56)
	v_fmac_f32_e32 v28, v109, v173
	v_fmac_f32_e32 v29, v109, v181
	v_fmac_f32_e32 v43, v109, v189
	ds_read_b128 v[166:169], v65 offset:32
	ds_read_b128 v[170:173], v65 offset:48
	ds_read_b128 v[174:177], v65 offset:4128
	ds_read_b128 v[178:181], v65 offset:4144
	ds_read_b128 v[182:185], v65 offset:8224
	ds_read_b128 v[186:189], v65 offset:8240
	s_waitcnt lgkmcnt(0)
; __global__ void __launch_bounds__(NTHR, 2) mk_fwd(Args args) {
;     ...
;                 const int kq = tid >> 7, nn = tid & 127; float a0 = 0.f, a1 = 0.f, a2 = 0.f;
;                 const float* wp = ap->in[I_WMOD] + ((size_t)l * 1024 + kq * 256) * 6144 + n0 + nn;
; #pragma unroll 32
;                 for (int k = 0; k < 256; ++k) { const float w = wp[(size_t)k * 6144]; a0 += sv[kq * 256 + k] * w; a1 += sv[1024 + kq * 256 + k] * w; a2 += sv[2048 + kq * 256 + k] * w; }
;                 red[(kq * 3 + 0) * 128 + nn] = a0; red[(kq * 3 + 1) * 128 + nn] = a1; red[(kq * 3 + 2) * 128 + nn] = a2;
	s_waitcnt vmcnt(55)
	v_fmac_f32_e32 v28, v110, v166
	v_fmac_f32_e32 v29, v110, v174
	v_fmac_f32_e32 v43, v110, v182
	s_waitcnt vmcnt(54)
	v_fmac_f32_e32 v28, v111, v167
	v_fmac_f32_e32 v29, v111, v175
	v_fmac_f32_e32 v43, v111, v183
	s_waitcnt vmcnt(53)
	v_fmac_f32_e32 v28, v112, v168
	v_fmac_f32_e32 v29, v112, v176
	v_fmac_f32_e32 v43, v112, v184
	s_waitcnt vmcnt(52)
	v_fmac_f32_e32 v28, v113, v169
	v_fmac_f32_e32 v29, v113, v177
	v_fmac_f32_e32 v43, v113, v185
	s_waitcnt vmcnt(51)
	v_fmac_f32_e32 v28, v114, v170
	v_fmac_f32_e32 v29, v114, v178
	v_fmac_f32_e32 v43, v114, v186
	s_waitcnt vmcnt(50)
	v_fmac_f32_e32 v28, v115, v171
	v_fmac_f32_e32 v29, v115, v179
	v_fmac_f32_e32 v43, v115, v187
	s_waitcnt vmcnt(49)
	v_fmac_f32_e32 v28, v116, v172
	v_fmac_f32_e32 v29, v116, v180
	v_fmac_f32_e32 v43, v116, v188
	s_waitcnt vmcnt(48)
	v_fmac_f32_e32 v28, v117, v173
	v_fmac_f32_e32 v29, v117, v181
	v_fmac_f32_e32 v43, v117, v189
	ds_read_b128 v[166:169], v65 offset:64
	ds_read_b128 v[170:173], v65 offset:80
	ds_read_b128 v[174:177], v65 offset:4160
	ds_read_b128 v[178:181], v65 offset:4176
	ds_read_b128 v[182:185], v65 offset:8256
	ds_read_b128 v[186:189], v65 offset:8272
	s_waitcnt lgkmcnt(0)
	s_waitcnt vmcnt(47)
	v_fmac_f32_e32 v28, v118, v166
	v_fmac_f32_e32 v29, v118, v174
	v_fmac_f32_e32 v43, v118, v182
	s_waitcnt vmcnt(46)
	v_fmac_f32_e32 v28, v119, v167
	v_fmac_f32_e32 v29, v119, v175
	v_fmac_f32_e32 v43, v119, v183
	s_waitcnt vmcnt(45)
	v_fmac_f32_e32 v28, v120, v168
	v_fmac_f32_e32 v29, v120, v176
	v_fmac_f32_e32 v43, v120, v184
	s_waitcnt vmcnt(44)
	v_fmac_f32_e32 v28, v121, v169
	v_fmac_f32_e32 v29, v121, v177
	v_fmac_f32_e32 v43, v121, v185
	s_waitcnt vmcnt(43)
	v_fmac_f32_e32 v28, v122, v170
	v_fmac_f32_e32 v29, v122, v178
	v_fmac_f32_e32 v43, v122, v186
	s_waitcnt vmcnt(42)
	v_fmac_f32_e32 v28, v123, v171
	v_fmac_f32_e32 v29, v123, v179
	v_fmac_f32_e32 v43, v123, v187
	s_waitcnt vmcnt(41)
	v_fmac_f32_e32 v28, v124, v172
	v_fmac_f32_e32 v29, v124, v180
	v_fmac_f32_e32 v43, v124, v188
	s_waitcnt vmcnt(40)
	v_fmac_f32_e32 v28, v125, v173
	v_fmac_f32_e32 v29, v125, v181
	v_fmac_f32_e32 v43, v125, v189
	ds_read_b128 v[166:169], v65 offset:96
	ds_read_b128 v[170:173], v65 offset:112
	ds_read_b128 v[174:177], v65 offset:4192
	ds_read_b128 v[178:181], v65 offset:4208
	ds_read_b128 v[182:185], v65 offset:8288
	ds_read_b128 v[186:189], v65 offset:8304
	s_waitcnt lgkmcnt(0)
	s_waitcnt vmcnt(39)
	v_fmac_f32_e32 v28, v126, v166
	v_fmac_f32_e32 v29, v126, v174
	v_fmac_f32_e32 v43, v126, v182
	s_waitcnt vmcnt(38)
	v_fmac_f32_e32 v28, v127, v167
	v_fmac_f32_e32 v29, v127, v175
	v_fmac_f32_e32 v43, v127, v183
	s_waitcnt vmcnt(37)
	v_fmac_f32_e32 v28, v128, v168
	v_fmac_f32_e32 v29, v128, v176
	v_fmac_f32_e32 v43, v128, v184
	s_waitcnt vmcnt(36)
	v_fmac_f32_e32 v28, v129, v169
	v_fmac_f32_e32 v29, v129, v177
	v_fmac_f32_e32 v43, v129, v185
	s_waitcnt vmcnt(35)
	v_fmac_f32_e32 v28, v130, v170
	v_fmac_f32_e32 v29, v130, v178
	v_fmac_f32_e32 v43, v130, v186
	s_waitcnt vmcnt(34)
	v_fmac_f32_e32 v28, v131, v171
	v_fmac_f32_e32 v29, v131, v179
	v_fmac_f32_e32 v43, v131, v187
	s_waitcnt vmcnt(33)
	v_fmac_f32_e32 v28, v132, v172
	v_fmac_f32_e32 v29, v132, v180
	v_fmac_f32_e32 v43, v132, v188
	s_waitcnt vmcnt(32)
	v_fmac_f32_e32 v28, v133, v173
	v_fmac_f32_e32 v29, v133, v181
	v_fmac_f32_e32 v43, v133, v189
	v_add_u32_e32 v65, 0x80, v65
	ds_read_b128 v[166:169], v65 offset:0
	ds_read_b128 v[170:173], v65 offset:16
	ds_read_b128 v[174:177], v65 offset:4096
	ds_read_b128 v[178:181], v65 offset:4112
	ds_read_b128 v[182:185], v65 offset:8192
	ds_read_b128 v[186:189], v65 offset:8208
	s_waitcnt lgkmcnt(0)
	s_waitcnt vmcnt(31)
	v_fmac_f32_e32 v28, v134, v166
	v_fmac_f32_e32 v29, v134, v174
	v_fmac_f32_e32 v43, v134, v182
	s_waitcnt vmcnt(30)
	v_fmac_f32_e32 v28, v135, v167
	v_fmac_f32_e32 v29, v135, v175
	v_fmac_f32_e32 v43, v135, v183
	s_waitcnt vmcnt(29)
	v_fmac_f32_e32 v28, v136, v168
	v_fmac_f32_e32 v29, v136, v176
	v_fmac_f32_e32 v43, v136, v184
	s_waitcnt vmcnt(28)
	v_fmac_f32_e32 v28, v137, v169
	v_fmac_f32_e32 v29, v137, v177
	v_fmac_f32_e32 v43, v137, v185
	s_waitcnt vmcnt(27)
	v_fmac_f32_e32 v28, v138, v170
	v_fmac_f32_e32 v29, v138, v178
	v_fmac_f32_e32 v43, v138, v186
	s_waitcnt vmcnt(26)
	v_fmac_f32_e32 v28, v139, v171
	v_fmac_f32_e32 v29, v139, v179
	v_fmac_f32_e32 v43, v139, v187
	s_waitcnt vmcnt(25)
	v_fmac_f32_e32 v28, v140, v172
	v_fmac_f32_e32 v29, v140, v180
	v_fmac_f32_e32 v43, v140, v188
	s_waitcnt vmcnt(24)
; __global__ void __launch_bounds__(NTHR, 2) mk_fwd(Args args) {
;     ...
;                 for (int k = 0; k < 256; ++k) { const float w = wp[(size_t)k * 6144]; a0 += sv[kq * 256 + k] * w; a1 += sv[1024 + kq * 256 + k] * w; a2 += sv[2048 + kq * 256 + k] * w; }
;                 red[(kq * 3 + 0) * 128 + nn] = a0; red[(kq * 3 + 1) * 128 + nn] = a1; red[(kq * 3 + 2) * 128 + nn] = a2;
;                 __syncthreads();
;                 if (tid < 384) { const int r = tid >> 7, n2 = tid & 127; float a = ap->in[I_BMOD][l * 6144 + n0 + n2];
;                     for (int q = 0; q < 4; ++q) a += red[(q * 3 + r) * 128 + n2];
;                     MOD[(l * 3 + r) * 6144 + n0 + n2] = a; }
	v_fmac_f32_e32 v28, v141, v173
	v_fmac_f32_e32 v29, v141, v181
	v_fmac_f32_e32 v43, v141, v189
	ds_read_b128 v[166:169], v65 offset:32
	ds_read_b128 v[170:173], v65 offset:48
	ds_read_b128 v[174:177], v65 offset:4128
	ds_read_b128 v[178:181], v65 offset:4144
	ds_read_b128 v[182:185], v65 offset:8224
	ds_read_b128 v[186:189], v65 offset:8240
	s_waitcnt lgkmcnt(0)
	s_waitcnt vmcnt(23)
	v_fmac_f32_e32 v28, v142, v166
	v_fmac_f32_e32 v29, v142, v174
	v_fmac_f32_e32 v43, v142, v182
	s_waitcnt vmcnt(22)
	v_fmac_f32_e32 v28, v143, v167
	v_fmac_f32_e32 v29, v143, v175
	v_fmac_f32_e32 v43, v143, v183
	s_waitcnt vmcnt(21)
	v_fmac_f32_e32 v28, v144, v168
	v_fmac_f32_e32 v29, v144, v176
	v_fmac_f32_e32 v43, v144, v184
	s_waitcnt vmcnt(20)
	v_fmac_f32_e32 v28, v145, v169
	v_fmac_f32_e32 v29, v145, v177
	v_fmac_f32_e32 v43, v145, v185
	s_waitcnt vmcnt(19)
	v_fmac_f32_e32 v28, v146, v170
	v_fmac_f32_e32 v29, v146, v178
	v_fmac_f32_e32 v43, v146, v186
	s_waitcnt vmcnt(18)
	v_fmac_f32_e32 v28, v147, v171
	v_fmac_f32_e32 v29, v147, v179
	v_fmac_f32_e32 v43, v147, v187
	s_waitcnt vmcnt(17)
	v_fmac_f32_e32 v28, v148, v172
	v_fmac_f32_e32 v29, v148, v180
	v_fmac_f32_e32 v43, v148, v188
	s_waitcnt vmcnt(16)
	v_fmac_f32_e32 v28, v149, v173
	v_fmac_f32_e32 v29, v149, v181
	v_fmac_f32_e32 v43, v149, v189
	ds_read_b128 v[166:169], v65 offset:64
	ds_read_b128 v[170:173], v65 offset:80
	ds_read_b128 v[174:177], v65 offset:4160
	ds_read_b128 v[178:181], v65 offset:4176
	ds_read_b128 v[182:185], v65 offset:8256
	ds_read_b128 v[186:189], v65 offset:8272
	s_waitcnt lgkmcnt(0)
	s_waitcnt vmcnt(15)
	v_fmac_f32_e32 v28, v150, v166
	v_fmac_f32_e32 v29, v150, v174
	v_fmac_f32_e32 v43, v150, v182
	s_waitcnt vmcnt(14)
	v_fmac_f32_e32 v28, v151, v167
	v_fmac_f32_e32 v29, v151, v175
	v_fmac_f32_e32 v43, v151, v183
	s_waitcnt vmcnt(13)
	v_fmac_f32_e32 v28, v152, v168
	v_fmac_f32_e32 v29, v152, v176
	v_fmac_f32_e32 v43, v152, v184
	s_waitcnt vmcnt(12)
	v_fmac_f32_e32 v28, v153, v169
	v_fmac_f32_e32 v29, v153, v177
	v_fmac_f32_e32 v43, v153, v185
	s_waitcnt vmcnt(11)
	v_fmac_f32_e32 v28, v154, v170
	v_fmac_f32_e32 v29, v154, v178
	v_fmac_f32_e32 v43, v154, v186
	s_waitcnt vmcnt(10)
	v_fmac_f32_e32 v28, v155, v171
	v_fmac_f32_e32 v29, v155, v179
	v_fmac_f32_e32 v43, v155, v187
	s_waitcnt vmcnt(9)
	v_fmac_f32_e32 v28, v156, v172
	v_fmac_f32_e32 v29, v156, v180
	v_fmac_f32_e32 v43, v156, v188
	s_waitcnt vmcnt(8)
	v_fmac_f32_e32 v28, v157, v173
	v_fmac_f32_e32 v29, v157, v181
	v_fmac_f32_e32 v43, v157, v189
	ds_read_b128 v[166:169], v65 offset:96
	ds_read_b128 v[170:173], v65 offset:112
	ds_read_b128 v[174:177], v65 offset:4192
	ds_read_b128 v[178:181], v65 offset:4208
	ds_read_b128 v[182:185], v65 offset:8288
	ds_read_b128 v[186:189], v65 offset:8304
	s_waitcnt lgkmcnt(0)
	s_waitcnt vmcnt(7)
	v_fmac_f32_e32 v28, v158, v166
	v_fmac_f32_e32 v29, v158, v174
	v_fmac_f32_e32 v43, v158, v182
	s_waitcnt vmcnt(6)
	v_fmac_f32_e32 v28, v159, v167
	v_fmac_f32_e32 v29, v159, v175
	v_fmac_f32_e32 v43, v159, v183
	s_waitcnt vmcnt(5)
	v_fmac_f32_e32 v28, v160, v168
	v_fmac_f32_e32 v29, v160, v176
	v_fmac_f32_e32 v43, v160, v184
	s_waitcnt vmcnt(4)
	v_fmac_f32_e32 v28, v161, v169
	v_fmac_f32_e32 v29, v161, v177
	v_fmac_f32_e32 v43, v161, v185
	s_waitcnt vmcnt(3)
	v_fmac_f32_e32 v28, v162, v170
	v_fmac_f32_e32 v29, v162, v178
	v_fmac_f32_e32 v43, v162, v186
	s_waitcnt vmcnt(2)
	v_fmac_f32_e32 v28, v163, v171
	v_fmac_f32_e32 v29, v163, v179
	v_fmac_f32_e32 v43, v163, v187
	s_waitcnt vmcnt(1)
	v_fmac_f32_e32 v28, v164, v172
	v_fmac_f32_e32 v29, v164, v180
	v_fmac_f32_e32 v43, v164, v188
	s_waitcnt vmcnt(0)
	v_fmac_f32_e32 v28, v165, v173
	v_fmac_f32_e32 v29, v165, v181
	v_fmac_f32_e32 v43, v165, v189
	v_add_u32_e32 v65, 0x80, v65
	ds_write2st64_b32 v64, v28, v29 offset0:48 offset1:50
	ds_write_b32 v64, v43 offset:13312
	s_waitcnt lgkmcnt(0)
	s_barrier
	s_and_saveexec_b64 s[10:11], s[40:41]
	s_cbranch_execz .LBB0_2223
	s_load_dwordx2 s[14:15], s[6:7], 0x28
	s_mul_i32 s1, s0, 0x1800
	s_add_i32 s1, s1, s2
	v_or_b32_e32 v0, s1, v42
	v_ashrrev_i32_e32 v1, 31, v0
	s_waitcnt lgkmcnt(0)
	v_lshl_add_u64 v[0:1], v[0:1], 2, s[14:15]
	global_load_dword v6, v[0:1], off
	ds_read2st64_b32 v[0:1], v41 offset0:48 offset1:54
	ds_read2st64_b32 v[2:3], v41 offset0:60 offset1:66
	v_mad_u64_u32 v[4:5], s[0:1], s0, 3, v[38:39]
	v_mul_lo_u32 v4, v4, s85
	v_add_u32_e32 v4, s2, v4
	v_or_b32_e32 v4, v4, v42
	v_ashrrev_i32_e32 v5, 31, v4
	s_waitcnt vmcnt(0) lgkmcnt(1)
	v_add_f32_e32 v0, v6, v0
	v_add_f32_e32 v0, v0, v1
	s_waitcnt lgkmcnt(0)
	v_add_f32_e32 v0, v0, v2
	v_add_f32_e32 v2, v0, v3
	v_lshl_add_u64 v[0:1], v[4:5], 2, s[4:5]
	global_store_dword v[0:1], v2, off
	s_branch .LBB0_2223
